# GEMM K-loops: the other 6-load segment also split 4/4 (its two A loads issued at the top of the next iteration), closing wait vmcnt(6)
# speedup vs baseline: 1.0142x; 1.0002x over previous
; #define PG8_STAGE(bufoff, gbase, voff) do { _Pragma("unroll") for (int _i = 0; _i < 2; ++_i) \
;         __builtin_amdgcn_global_load_lds((const unsigned*)((const char*)(gbase) + (voff)[_i]), (PG8_LAS unsigned*)(lds + (bufoff) + ldsw + _i * 8192), 16, 0, 0); } while (0)
; #define PG8_LDA(dst, b, h) do { _Pragma("unroll") for (int m = 0; m < 4; ++m) _Pragma("unroll") for (int k = 0; k < 2; ++k) dst[m][k] = *(const PG8_LAS bf16x8*)(lds + PG8_SA(b, h) + aoff + m * 2048 + k * 1024); } while (0)
; #define PG8_LDB(dst, b, h) do { _Pragma("unroll") for (int n = 0; n < 2; ++n) _Pragma("unroll") for (int k = 0; k < 2; ++k) dst[n][k] = *(const PG8_LAS bf16x8*)(lds + PG8_SB(b, h) + boff + n * 2048 + k * 1024); } while (0)
; #define PG8_MMA(ai, bj, At, Bt) do { __builtin_amdgcn_s_setprio(1); _Pragma("unroll") for (int m = 0; m < 4; ++m) _Pragma("unroll") for (int n = 0; n < 2; ++n) _Pragma("unroll") for (int k = 0; k < 2; ++k) \
;         acc[ai][bj][m][n] = __builtin_amdgcn_mfma_f32_16x16x32_bf16(Bt[n][k], At[m][k], acc[ai][bj][m][n], 0, 0, 0); __builtin_amdgcn_s_setprio(0); } while (0)
; #define PG8_WAIT_V(n) asm volatile("s_waitcnt vmcnt(" #n ")" ::: "memory")
; #define PG8_WAIT_L(n) asm volatile("s_waitcnt lgkmcnt(" #n ")" ::: "memory")
; #define PG8_BAR __builtin_amdgcn_s_barrier()
; #define PG8_SCHED __builtin_amdgcn_sched_barrier(0)
; template <class Epi, class Sched, bool ALIGN_EPI = false, bool SP2 = false>
; __device__ __forceinline__ void gemm_phase(PG8_LAS unsigned char* lds, const Gemm g, const Sched& S, const Epi& E) {
;     ...
;             PG8_LDB(B0, 0, 0); PG8_LDB(B1, 0, 1); PG8_SCHED; PG8_LDA(At, 0, 0); PG8_STAGE(PG8_SA(1, 1), a1 + hstep, voffA);
;             PG8_WAIT_V(8); PG8_WAIT_L(0); PG8_BAR; PG8_MMA(0, 0, At, B0); PG8_MMA(0, 1, At, B1); PG8_BAR; PG8_SCHED;
;             PG8_LDA(At, 0, 1); PG8_STAGE(PG8_SB(0, 0), b2, voffB); PG8_STAGE(PG8_SB(0, 1), b2 + hstep, voffB); PG8_STAGE(PG8_SA(0, 0), a2, voffA);
;             PG8_WAIT_V(8); PG8_WAIT_L(0); PG8_BAR; PG8_MMA(1, 0, At, B0); PG8_MMA(1, 1, At, B1); PG8_BAR; PG8_SCHED;
.LBB0_124:
	ds_read_b128 v[150:153], v161
	ds_read_b128 v[154:157], v161 offset:1024
	ds_read_b128 v[166:169], v161 offset:2048
	ds_read_b128 v[170:173], v161 offset:3072
	ds_read_b128 v[174:177], v162
	ds_read_b128 v[178:181], v162 offset:1024
	ds_read_b128 v[182:185], v162 offset:2048
	ds_read_b128 v[186:189], v162 offset:3072
	s_add_u32 s4, s36, 0xfff80080
	s_addc_u32 s5, s37, -1
	s_cmp_eq_u32 s69, 28
	s_cselect_b32 s41, s9, s5
	s_cselect_b32 s40, s27, s4
	s_cselect_b32 s39, s25, s68
	s_cselect_b32 s38, s35, s67
	s_add_i32 m0, s58, 0x80
	s_nop 0
	global_load_lds_dwordx4 v130, s[4:5] offset:-128
	s_add_i32 m0, s59, 0x80
	s_nop 0
	global_load_lds_dwordx4 v134, s[4:5] offset:-128
	s_add_i32 m0, s49, 0xc000
	ds_read_b128 v[190:193], v163
	ds_read_b128 v[194:197], v163 offset:1024
	ds_read_b128 v[198:201], v163 offset:2048
	ds_read_b128 v[202:205], v163 offset:3072
	ds_read_b128 v[206:209], v163 offset:4096
	ds_read_b128 v[210:213], v163 offset:5120
	ds_read_b128 v[214:217], v163 offset:6144
	ds_read_b128 v[218:221], v163 offset:7168
	global_load_lds_dwordx4 v140, s[36:37]
	s_add_i32 m0, s49, 0xe000
	s_nop 0
	global_load_lds_dwordx4 v142, s[36:37]
	s_waitcnt vmcnt(8)
	s_waitcnt lgkmcnt(0)
	s_barrier
	s_setprio 1
	s_waitcnt lgkmcnt(0)
	v_mfma_f32_16x16x32_bf16 v[126:129], v[150:153], v[190:193], v[126:129]
	v_mfma_f32_16x16x32_bf16 v[122:125], v[166:169], v[190:193], v[122:125]
	v_mfma_f32_16x16x32_bf16 v[110:113], v[150:153], v[198:201], v[110:113]
	v_mfma_f32_16x16x32_bf16 v[106:109], v[166:169], v[198:201], v[106:109]
	v_mfma_f32_16x16x32_bf16 v[94:97], v[150:153], v[206:209], v[94:97]
	v_mfma_f32_16x16x32_bf16 v[90:93], v[166:169], v[206:209], v[90:93]
	v_mfma_f32_16x16x32_bf16 v[78:81], v[150:153], v[214:217], v[78:81]
	v_mfma_f32_16x16x32_bf16 v[74:77], v[166:169], v[214:217], v[74:77]
	v_mfma_f32_16x16x32_bf16 v[126:129], v[154:157], v[194:197], v[126:129]
	v_mfma_f32_16x16x32_bf16 v[122:125], v[170:173], v[194:197], v[122:125]
	v_mfma_f32_16x16x32_bf16 v[110:113], v[154:157], v[202:205], v[110:113]
	v_mfma_f32_16x16x32_bf16 v[106:109], v[170:173], v[202:205], v[106:109]
	v_mfma_f32_16x16x32_bf16 v[94:97], v[154:157], v[210:213], v[94:97]
	v_mfma_f32_16x16x32_bf16 v[90:93], v[170:173], v[210:213], v[90:93]
	v_mfma_f32_16x16x32_bf16 v[78:81], v[154:157], v[218:221], v[78:81]
	v_mfma_f32_16x16x32_bf16 v[74:77], v[170:173], v[218:221], v[74:77]
	s_setprio 0
	s_setprio 1
	v_mfma_f32_16x16x32_bf16 v[118:121], v[174:177], v[190:193], v[118:121]
	v_mfma_f32_16x16x32_bf16 v[114:117], v[182:185], v[190:193], v[114:117]
	v_mfma_f32_16x16x32_bf16 v[102:105], v[174:177], v[198:201], v[102:105]
	v_mfma_f32_16x16x32_bf16 v[98:101], v[182:185], v[198:201], v[98:101]
	v_mfma_f32_16x16x32_bf16 v[86:89], v[174:177], v[206:209], v[86:89]
	v_mfma_f32_16x16x32_bf16 v[82:85], v[182:185], v[206:209], v[82:85]
	v_mfma_f32_16x16x32_bf16 v[70:73], v[174:177], v[214:217], v[70:73]
	v_mfma_f32_16x16x32_bf16 v[66:69], v[182:185], v[214:217], v[66:69]
	v_mfma_f32_16x16x32_bf16 v[118:121], v[178:181], v[194:197], v[118:121]
	v_mfma_f32_16x16x32_bf16 v[114:117], v[186:189], v[194:197], v[114:117]
	v_mfma_f32_16x16x32_bf16 v[102:105], v[178:181], v[202:205], v[102:105]
	v_mfma_f32_16x16x32_bf16 v[98:101], v[186:189], v[202:205], v[98:101]
	v_mfma_f32_16x16x32_bf16 v[86:89], v[178:181], v[210:213], v[86:89]
	v_mfma_f32_16x16x32_bf16 v[82:85], v[186:189], v[210:213], v[82:85]
	v_mfma_f32_16x16x32_bf16 v[70:73], v[178:181], v[218:221], v[70:73]
	v_mfma_f32_16x16x32_bf16 v[66:69], v[186:189], v[218:221], v[66:69]
	s_setprio 0
	s_barrier
	s_add_i32 s4, s64, s48
	s_mov_b32 m0, s4
	ds_read_b128 v[190:193], v163 offset:16384
	ds_read_b128 v[194:197], v163 offset:17408
	ds_read_b128 v[198:201], v163 offset:18432
	ds_read_b128 v[202:205], v163 offset:19456
	ds_read_b128 v[206:209], v163 offset:20480
	ds_read_b128 v[210:213], v163 offset:21504
	ds_read_b128 v[214:217], v163 offset:22528
	ds_read_b128 v[218:221], v163 offset:23552
	global_load_lds_dwordx4 v132, s[38:39]
	s_add_i32 m0, s4, 0x2000
	s_add_u32 s70, s38, 0x80000
	s_addc_u32 s71, s39, 0
	s_add_i32 s4, s65, s48
	global_load_lds_dwordx4 v136, s[38:39]
	s_mov_b32 m0, s4
	s_nop 0
	global_load_lds_dwordx4 v132, s[70:71]
	s_add_i32 m0, s4, 0x2000
	s_nop 0
	global_load_lds_dwordx4 v136, s[70:71]
	s_waitcnt vmcnt(6)
	s_waitcnt lgkmcnt(0)
	s_barrier
	s_setprio 1
	s_waitcnt lgkmcnt(0)
	v_mfma_f32_16x16x32_bf16 v[62:65], v[150:153], v[190:193], v[62:65]
	v_mfma_f32_16x16x32_bf16 v[58:61], v[166:169], v[190:193], v[58:61]
	v_mfma_f32_16x16x32_bf16 v[46:49], v[150:153], v[198:201], v[46:49]
	v_mfma_f32_16x16x32_bf16 v[42:45], v[166:169], v[198:201], v[42:45]
	v_mfma_f32_16x16x32_bf16 v[30:33], v[150:153], v[206:209], v[30:33]
	v_mfma_f32_16x16x32_bf16 v[26:29], v[166:169], v[206:209], v[26:29]
	v_mfma_f32_16x16x32_bf16 v[14:17], v[150:153], v[214:217], v[14:17]
	v_mfma_f32_16x16x32_bf16 v[10:13], v[166:169], v[214:217], v[10:13]
	v_mfma_f32_16x16x32_bf16 v[62:65], v[154:157], v[194:197], v[62:65]
	v_mfma_f32_16x16x32_bf16 v[58:61], v[170:173], v[194:197], v[58:61]
	v_mfma_f32_16x16x32_bf16 v[46:49], v[154:157], v[202:205], v[46:49]
	v_mfma_f32_16x16x32_bf16 v[42:45], v[170:173], v[202:205], v[42:45]
	v_mfma_f32_16x16x32_bf16 v[30:33], v[154:157], v[210:213], v[30:33]
	v_mfma_f32_16x16x32_bf16 v[26:29], v[170:173], v[210:213], v[26:29]
	v_mfma_f32_16x16x32_bf16 v[14:17], v[154:157], v[218:221], v[14:17]
	v_mfma_f32_16x16x32_bf16 v[10:13], v[170:173], v[218:221], v[10:13]
	s_setprio 0
	s_setprio 1
	v_mfma_f32_16x16x32_bf16 v[54:57], v[174:177], v[190:193], v[54:57]
	v_mfma_f32_16x16x32_bf16 v[50:53], v[182:185], v[190:193], v[50:53]
	v_mfma_f32_16x16x32_bf16 v[38:41], v[174:177], v[198:201], v[38:41]
	v_mfma_f32_16x16x32_bf16 v[34:37], v[182:185], v[198:201], v[34:37]
	v_mfma_f32_16x16x32_bf16 v[22:25], v[174:177], v[206:209], v[22:25]
	v_mfma_f32_16x16x32_bf16 v[18:21], v[182:185], v[206:209], v[18:21]
	v_mfma_f32_16x16x32_bf16 v[6:9], v[174:177], v[214:217], v[6:9]
	v_mfma_f32_16x16x32_bf16 v[2:5], v[182:185], v[214:217], v[2:5]
	v_mfma_f32_16x16x32_bf16 v[54:57], v[178:181], v[194:197], v[54:57]
	v_mfma_f32_16x16x32_bf16 v[50:53], v[186:189], v[194:197], v[50:53]
	v_mfma_f32_16x16x32_bf16 v[38:41], v[178:181], v[202:205], v[38:41]
	v_mfma_f32_16x16x32_bf16 v[34:37], v[186:189], v[202:205], v[34:37]
	v_mfma_f32_16x16x32_bf16 v[22:25], v[178:181], v[210:213], v[22:25]
	v_mfma_f32_16x16x32_bf16 v[18:21], v[186:189], v[210:213], v[18:21]
	v_mfma_f32_16x16x32_bf16 v[6:9], v[178:181], v[218:221], v[6:9]
	v_mfma_f32_16x16x32_bf16 v[2:5], v[186:189], v[218:221], v[2:5]
	s_setprio 0
	s_barrier
; #define PG8_STAGE(bufoff, gbase, voff) do { _Pragma("unroll") for (int _i = 0; _i < 2; ++_i) \
;         __builtin_amdgcn_global_load_lds((const unsigned*)((const char*)(gbase) + (voff)[_i]), (PG8_LAS unsigned*)(lds + (bufoff) + ldsw + _i * 8192), 16, 0, 0); } while (0)
; #define PG8_LDA(dst, b, h) do { _Pragma("unroll") for (int m = 0; m < 4; ++m) _Pragma("unroll") for (int k = 0; k < 2; ++k) dst[m][k] = *(const PG8_LAS bf16x8*)(lds + PG8_SA(b, h) + aoff + m * 2048 + k * 1024); } while (0)
; #define PG8_LDB(dst, b, h) do { _Pragma("unroll") for (int n = 0; n < 2; ++n) _Pragma("unroll") for (int k = 0; k < 2; ++k) dst[n][k] = *(const PG8_LAS bf16x8*)(lds + PG8_SB(b, h) + boff + n * 2048 + k * 1024); } while (0)
; #define PG8_MMA(ai, bj, At, Bt) do { __builtin_amdgcn_s_setprio(1); _Pragma("unroll") for (int m = 0; m < 4; ++m) _Pragma("unroll") for (int n = 0; n < 2; ++n) _Pragma("unroll") for (int k = 0; k < 2; ++k) \
;         acc[ai][bj][m][n] = __builtin_amdgcn_mfma_f32_16x16x32_bf16(Bt[n][k], At[m][k], acc[ai][bj][m][n], 0, 0, 0); __builtin_amdgcn_s_setprio(0); } while (0)
; #define PG8_WAIT_V(n) asm volatile("s_waitcnt vmcnt(" #n ")" ::: "memory")
; #define PG8_WAIT_L(n) asm volatile("s_waitcnt lgkmcnt(" #n ")" ::: "memory")
; #define PG8_BAR __builtin_amdgcn_s_barrier()
; #define PG8_SCHED __builtin_amdgcn_sched_barrier(0)
; template <class Epi, class Sched, bool ALIGN_EPI = false, bool SP2 = false>
; __device__ __forceinline__ void gemm_phase(PG8_LAS unsigned char* lds, const Gemm g, const Sched& S, const Epi& E) {
;     ...
;             PG8_LDB(B0, 1, 0); PG8_LDB(B1, 1, 1); PG8_SCHED; PG8_LDA(At, 1, 0); PG8_STAGE(PG8_SA(0, 1), a2 + hstep, voffA);
;             PG8_WAIT_V(8); PG8_WAIT_L(0); PG8_BAR; PG8_MMA(0, 0, At, B0); PG8_MMA(0, 1, At, B1); PG8_BAR; PG8_SCHED;
;             PG8_LDA(At, 1, 1); PG8_STAGE(PG8_SB(1, 0), b3, voffB); PG8_STAGE(PG8_SB(1, 1), b3 + hstep, voffB); PG8_STAGE(PG8_SA(1, 0), a3, voffA);
;             PG8_WAIT_V(8); PG8_WAIT_L(0); PG8_BAR; PG8_MMA(1, 0, At, B0); PG8_MMA(1, 1, At, B1); PG8_BAR; PG8_SCHED;
	s_add_i32 s4, 0, 0x18000
	v_add_u32_e32 v138, s4, v159
	s_add_i32 s5, 0, 0x1c000
	ds_read_b128 v[150:153], v138
	ds_read_b128 v[154:157], v138 offset:1024
	ds_read_b128 v[166:169], v138 offset:2048
	ds_read_b128 v[170:173], v138 offset:3072
	v_add_u32_e32 v138, s5, v159
	ds_read_b128 v[174:177], v138
	ds_read_b128 v[178:181], v138 offset:1024
	ds_read_b128 v[182:185], v138 offset:2048
	ds_read_b128 v[186:189], v138 offset:3072
	s_add_u32 s70, s40, 0x80000
	s_addc_u32 s71, s41, 0
	s_mov_b32 m0, s49
	s_nop 0
	global_load_lds_dwordx4 v130, s[40:41]
	s_mov_b32 m0, s50
	s_nop 0
	global_load_lds_dwordx4 v134, s[40:41]
	s_mov_b32 m0, s51
	ds_read_b128 v[190:193], v163 offset:32768
	ds_read_b128 v[194:197], v163 offset:33792
	ds_read_b128 v[198:201], v163 offset:34816
	ds_read_b128 v[202:205], v163 offset:35840
	ds_read_b128 v[206:209], v163 offset:36864
	ds_read_b128 v[210:213], v163 offset:37888
	ds_read_b128 v[214:217], v163 offset:38912
	ds_read_b128 v[218:221], v163 offset:39936
	global_load_lds_dwordx4 v130, s[70:71]
	s_mov_b32 m0, s52
	s_nop 0
	global_load_lds_dwordx4 v134, s[70:71]
	s_waitcnt vmcnt(8)
	s_waitcnt lgkmcnt(0)
	s_barrier
	s_setprio 1
	s_waitcnt lgkmcnt(0)
	v_mfma_f32_16x16x32_bf16 v[126:129], v[150:153], v[190:193], v[126:129]
	v_mfma_f32_16x16x32_bf16 v[122:125], v[166:169], v[190:193], v[122:125]
	v_mfma_f32_16x16x32_bf16 v[110:113], v[150:153], v[198:201], v[110:113]
	v_mfma_f32_16x16x32_bf16 v[106:109], v[166:169], v[198:201], v[106:109]
	v_mfma_f32_16x16x32_bf16 v[94:97], v[150:153], v[206:209], v[94:97]
	v_mfma_f32_16x16x32_bf16 v[90:93], v[166:169], v[206:209], v[90:93]
	v_mfma_f32_16x16x32_bf16 v[78:81], v[150:153], v[214:217], v[78:81]
	v_mfma_f32_16x16x32_bf16 v[74:77], v[166:169], v[214:217], v[74:77]
	v_mfma_f32_16x16x32_bf16 v[126:129], v[154:157], v[194:197], v[126:129]
	v_mfma_f32_16x16x32_bf16 v[122:125], v[170:173], v[194:197], v[122:125]
	v_mfma_f32_16x16x32_bf16 v[110:113], v[154:157], v[202:205], v[110:113]
	v_mfma_f32_16x16x32_bf16 v[106:109], v[170:173], v[202:205], v[106:109]
	v_mfma_f32_16x16x32_bf16 v[94:97], v[154:157], v[210:213], v[94:97]
	v_mfma_f32_16x16x32_bf16 v[90:93], v[170:173], v[210:213], v[90:93]
	v_mfma_f32_16x16x32_bf16 v[78:81], v[154:157], v[218:221], v[78:81]
	v_mfma_f32_16x16x32_bf16 v[74:77], v[170:173], v[218:221], v[74:77]
	s_setprio 0
	s_setprio 1
	v_mfma_f32_16x16x32_bf16 v[118:121], v[174:177], v[190:193], v[118:121]
	v_mfma_f32_16x16x32_bf16 v[114:117], v[182:185], v[190:193], v[114:117]
	v_mfma_f32_16x16x32_bf16 v[102:105], v[174:177], v[198:201], v[102:105]
	v_mfma_f32_16x16x32_bf16 v[98:101], v[182:185], v[198:201], v[98:101]
	v_mfma_f32_16x16x32_bf16 v[86:89], v[174:177], v[206:209], v[86:89]
	v_mfma_f32_16x16x32_bf16 v[82:85], v[182:185], v[206:209], v[82:85]
	v_mfma_f32_16x16x32_bf16 v[70:73], v[174:177], v[214:217], v[70:73]
	v_mfma_f32_16x16x32_bf16 v[66:69], v[182:185], v[214:217], v[66:69]
	v_mfma_f32_16x16x32_bf16 v[118:121], v[178:181], v[194:197], v[118:121]
	v_mfma_f32_16x16x32_bf16 v[114:117], v[186:189], v[194:197], v[114:117]
	v_mfma_f32_16x16x32_bf16 v[102:105], v[178:181], v[202:205], v[102:105]
	v_mfma_f32_16x16x32_bf16 v[98:101], v[186:189], v[202:205], v[98:101]
	v_mfma_f32_16x16x32_bf16 v[86:89], v[178:181], v[210:213], v[86:89]
	v_mfma_f32_16x16x32_bf16 v[82:85], v[186:189], v[210:213], v[82:85]
	v_mfma_f32_16x16x32_bf16 v[70:73], v[178:181], v[218:221], v[70:73]
	v_mfma_f32_16x16x32_bf16 v[66:69], v[186:189], v[218:221], v[66:69]
	s_setprio 0
	s_barrier
	s_add_i32 s4, s4, s48
	s_add_i32 m0, s4, 0xffffff80
	ds_read_b128 v[190:193], v163 offset:49152
	ds_read_b128 v[194:197], v163 offset:50176
	ds_read_b128 v[198:201], v163 offset:51200
	ds_read_b128 v[202:205], v163 offset:52224
	ds_read_b128 v[206:209], v163 offset:53248
	ds_read_b128 v[210:213], v163 offset:54272
	ds_read_b128 v[214:217], v163 offset:55296
	ds_read_b128 v[218:221], v163 offset:56320
	global_load_lds_dwordx4 v132, s[38:39] offset:128
	s_add_i32 m0, s4, 0x1f80
	s_nop 0
	global_load_lds_dwordx4 v136, s[38:39] offset:128
	s_add_u32 s38, s38, 0x80080
	s_addc_u32 s39, s39, 0
	s_add_i32 s4, s5, s48
	s_mov_b32 m0, s4
	s_nop 0
	global_load_lds_dwordx4 v132, s[38:39]
	s_add_i32 m0, s4, 0x2000
	s_nop 0
	global_load_lds_dwordx4 v136, s[38:39]
	s_waitcnt vmcnt(6)
	s_waitcnt lgkmcnt(0)
	s_barrier
	s_setprio 1
	s_waitcnt lgkmcnt(0)
	v_mfma_f32_16x16x32_bf16 v[62:65], v[150:153], v[190:193], v[62:65]
	v_mfma_f32_16x16x32_bf16 v[58:61], v[166:169], v[190:193], v[58:61]
	v_mfma_f32_16x16x32_bf16 v[46:49], v[150:153], v[198:201], v[46:49]
	v_mfma_f32_16x16x32_bf16 v[42:45], v[166:169], v[198:201], v[42:45]
	v_mfma_f32_16x16x32_bf16 v[30:33], v[150:153], v[206:209], v[30:33]
	v_mfma_f32_16x16x32_bf16 v[26:29], v[166:169], v[206:209], v[26:29]
	v_mfma_f32_16x16x32_bf16 v[14:17], v[150:153], v[214:217], v[14:17]
	v_mfma_f32_16x16x32_bf16 v[10:13], v[166:169], v[214:217], v[10:13]
	v_mfma_f32_16x16x32_bf16 v[62:65], v[154:157], v[194:197], v[62:65]
	v_mfma_f32_16x16x32_bf16 v[58:61], v[170:173], v[194:197], v[58:61]
	v_mfma_f32_16x16x32_bf16 v[46:49], v[154:157], v[202:205], v[46:49]
	v_mfma_f32_16x16x32_bf16 v[42:45], v[170:173], v[202:205], v[42:45]
	v_mfma_f32_16x16x32_bf16 v[30:33], v[154:157], v[210:213], v[30:33]
	v_mfma_f32_16x16x32_bf16 v[26:29], v[170:173], v[210:213], v[26:29]
	v_mfma_f32_16x16x32_bf16 v[14:17], v[154:157], v[218:221], v[14:17]
	v_mfma_f32_16x16x32_bf16 v[10:13], v[170:173], v[218:221], v[10:13]
	s_setprio 0
	s_setprio 1
	v_mfma_f32_16x16x32_bf16 v[54:57], v[174:177], v[190:193], v[54:57]
	v_mfma_f32_16x16x32_bf16 v[50:53], v[182:185], v[190:193], v[50:53]
	v_mfma_f32_16x16x32_bf16 v[38:41], v[174:177], v[198:201], v[38:41]
	v_mfma_f32_16x16x32_bf16 v[34:37], v[182:185], v[198:201], v[34:37]
	v_mfma_f32_16x16x32_bf16 v[22:25], v[174:177], v[206:209], v[22:25]
	v_mfma_f32_16x16x32_bf16 v[18:21], v[182:185], v[206:209], v[18:21]
	v_mfma_f32_16x16x32_bf16 v[6:9], v[174:177], v[214:217], v[6:9]
	v_mfma_f32_16x16x32_bf16 v[2:5], v[182:185], v[214:217], v[2:5]
	v_mfma_f32_16x16x32_bf16 v[54:57], v[178:181], v[194:197], v[54:57]
	v_mfma_f32_16x16x32_bf16 v[50:53], v[186:189], v[194:197], v[50:53]
	v_mfma_f32_16x16x32_bf16 v[38:41], v[178:181], v[202:205], v[38:41]
	v_mfma_f32_16x16x32_bf16 v[34:37], v[186:189], v[202:205], v[34:37]
	v_mfma_f32_16x16x32_bf16 v[22:25], v[178:181], v[210:213], v[22:25]
	v_mfma_f32_16x16x32_bf16 v[18:21], v[186:189], v[210:213], v[18:21]
	v_mfma_f32_16x16x32_bf16 v[6:9], v[178:181], v[218:221], v[6:9]
	v_mfma_f32_16x16x32_bf16 v[2:5], v[186:189], v[218:221], v[2:5]
	s_setprio 0
	s_barrier
	s_add_i32 s69, s69, 2
	s_add_u32 s36, s36, 0x100
	s_addc_u32 s37, s37, 0
	s_add_u32 s67, s67, 0x100
	s_addc_u32 s68, s68, 0
	s_cmp_gt_u32 s69, 29
	s_cbranch_scc0 .LBB0_124
	s_and_b64 vcc, exec, s[22:23]
	s_cbranch_vccz .LBB0_127
	s_barrier

; #define PG8_STAGE(bufoff, gbase, voff) do { _Pragma("unroll") for (int _i = 0; _i < 2; ++_i) \
;         __builtin_amdgcn_global_load_lds((const unsigned*)((const char*)(gbase) + (voff)[_i]), (PG8_LAS unsigned*)(lds + (bufoff) + ldsw + _i * 8192), 16, 0, 0); } while (0)
; #define PG8_LDA(dst, b, h) do { _Pragma("unroll") for (int m = 0; m < 4; ++m) _Pragma("unroll") for (int k = 0; k < 2; ++k) dst[m][k] = *(const PG8_LAS bf16x8*)(lds + PG8_SA(b, h) + aoff + m * 2048 + k * 1024); } while (0)
; #define PG8_LDB(dst, b, h) do { _Pragma("unroll") for (int n = 0; n < 2; ++n) _Pragma("unroll") for (int k = 0; k < 2; ++k) dst[n][k] = *(const PG8_LAS bf16x8*)(lds + PG8_SB(b, h) + boff + n * 2048 + k * 1024); } while (0)
; #define PG8_MMA(ai, bj, At, Bt) do { __builtin_amdgcn_s_setprio(1); _Pragma("unroll") for (int m = 0; m < 4; ++m) _Pragma("unroll") for (int n = 0; n < 2; ++n) _Pragma("unroll") for (int k = 0; k < 2; ++k) \
;         acc[ai][bj][m][n] = __builtin_amdgcn_mfma_f32_16x16x32_bf16(Bt[n][k], At[m][k], acc[ai][bj][m][n], 0, 0, 0); __builtin_amdgcn_s_setprio(0); } while (0)
; #define PG8_WAIT_V(n) asm volatile("s_waitcnt vmcnt(" #n ")" ::: "memory")
; #define PG8_WAIT_L(n) asm volatile("s_waitcnt lgkmcnt(" #n ")" ::: "memory")
; #define PG8_BAR __builtin_amdgcn_s_barrier()
; #define PG8_SCHED __builtin_amdgcn_sched_barrier(0)
; template <class Epi, class Sched, bool ALIGN_EPI = false, bool SP2 = false>
; __device__ __forceinline__ void gemm_phase(PG8_LAS unsigned char* lds, const Gemm g, const Sched& S, const Epi& E) {
;     ...
;             PG8_LDB(B0, 0, 0); PG8_LDB(B1, 0, 1); PG8_SCHED; PG8_LDA(At, 0, 0); PG8_STAGE(PG8_SA(1, 1), a1 + hstep, voffA);
;             PG8_WAIT_V(8); PG8_WAIT_L(0); PG8_BAR; PG8_MMA(0, 0, At, B0); PG8_MMA(0, 1, At, B1); PG8_BAR; PG8_SCHED;
;             PG8_LDA(At, 0, 1); PG8_STAGE(PG8_SB(0, 0), b2, voffB); PG8_STAGE(PG8_SB(0, 1), b2 + hstep, voffB); PG8_STAGE(PG8_SA(0, 0), a2, voffA);
;             PG8_WAIT_V(8); PG8_WAIT_L(0); PG8_BAR; PG8_MMA(1, 0, At, B0); PG8_MMA(1, 1, At, B1); PG8_BAR; PG8_SCHED;
.LBB0_763:
	ds_read_b128 v[154:157], v150
	ds_read_b128 v[158:161], v150 offset:1024
	ds_read_b128 v[162:165], v150 offset:2048
	ds_read_b128 v[166:169], v150 offset:3072
	ds_read_b128 v[170:173], v151
	ds_read_b128 v[174:177], v151 offset:1024
	ds_read_b128 v[178:181], v151 offset:2048
	ds_read_b128 v[182:185], v151 offset:3072
	s_add_u32 s4, s40, 0xfff80080
	s_addc_u32 s5, s41, -1
	s_cmp_eq_u32 s78, 28
	s_cselect_b32 s51, s31, s5
	s_cselect_b32 s50, s74, s4
	s_cselect_b32 s49, s29, s77
	s_cselect_b32 s48, s75, s76
	s_add_i32 m0, s63, 0x80
	s_nop 0
	global_load_lds_dwordx4 v130, s[4:5] offset:-128
	s_add_i32 m0, s64, 0x80
	s_nop 0
	global_load_lds_dwordx4 v134, s[4:5] offset:-128
	s_add_i32 m0, s39, 0xc000
	ds_read_b128 v[186:189], v152
	ds_read_b128 v[190:193], v152 offset:1024
	ds_read_b128 v[194:197], v152 offset:2048
	ds_read_b128 v[198:201], v152 offset:3072
	ds_read_b128 v[202:205], v152 offset:4096
	ds_read_b128 v[206:209], v152 offset:5120
	ds_read_b128 v[210:213], v152 offset:6144
	ds_read_b128 v[214:217], v152 offset:7168
	global_load_lds_dwordx4 v138, s[40:41]
	s_add_i32 m0, s39, 0xe000
	s_nop 0
	global_load_lds_dwordx4 v140, s[40:41]
	s_waitcnt vmcnt(8)
	s_waitcnt lgkmcnt(0)
	s_barrier
	s_setprio 1
	s_waitcnt lgkmcnt(0)
	v_mfma_f32_16x16x32_bf16 v[126:129], v[154:157], v[186:189], v[126:129]
	v_mfma_f32_16x16x32_bf16 v[122:125], v[162:165], v[186:189], v[122:125]
	v_mfma_f32_16x16x32_bf16 v[114:117], v[154:157], v[194:197], v[114:117]
	v_mfma_f32_16x16x32_bf16 v[106:109], v[162:165], v[194:197], v[106:109]
	v_mfma_f32_16x16x32_bf16 v[98:101], v[154:157], v[202:205], v[98:101]
	v_mfma_f32_16x16x32_bf16 v[90:93], v[162:165], v[202:205], v[90:93]
	v_mfma_f32_16x16x32_bf16 v[82:85], v[154:157], v[210:213], v[82:85]
	v_mfma_f32_16x16x32_bf16 v[74:77], v[162:165], v[210:213], v[74:77]
	v_mfma_f32_16x16x32_bf16 v[126:129], v[158:161], v[190:193], v[126:129]
	v_mfma_f32_16x16x32_bf16 v[122:125], v[166:169], v[190:193], v[122:125]
	v_mfma_f32_16x16x32_bf16 v[114:117], v[158:161], v[198:201], v[114:117]
	v_mfma_f32_16x16x32_bf16 v[106:109], v[166:169], v[198:201], v[106:109]
	v_mfma_f32_16x16x32_bf16 v[98:101], v[158:161], v[206:209], v[98:101]
	v_mfma_f32_16x16x32_bf16 v[90:93], v[166:169], v[206:209], v[90:93]
	v_mfma_f32_16x16x32_bf16 v[82:85], v[158:161], v[214:217], v[82:85]
	v_mfma_f32_16x16x32_bf16 v[74:77], v[166:169], v[214:217], v[74:77]
	s_setprio 0
	s_setprio 1
	v_mfma_f32_16x16x32_bf16 v[118:121], v[170:173], v[186:189], v[118:121]
	v_mfma_f32_16x16x32_bf16 v[110:113], v[178:181], v[186:189], v[110:113]
	v_mfma_f32_16x16x32_bf16 v[102:105], v[170:173], v[194:197], v[102:105]
	v_mfma_f32_16x16x32_bf16 v[94:97], v[178:181], v[194:197], v[94:97]
	v_mfma_f32_16x16x32_bf16 v[86:89], v[170:173], v[202:205], v[86:89]
	v_mfma_f32_16x16x32_bf16 v[78:81], v[178:181], v[202:205], v[78:81]
	v_mfma_f32_16x16x32_bf16 v[70:73], v[170:173], v[210:213], v[70:73]
	v_mfma_f32_16x16x32_bf16 v[66:69], v[178:181], v[210:213], v[66:69]
	v_mfma_f32_16x16x32_bf16 v[118:121], v[174:177], v[190:193], v[118:121]
	v_mfma_f32_16x16x32_bf16 v[110:113], v[182:185], v[190:193], v[110:113]
	v_mfma_f32_16x16x32_bf16 v[102:105], v[174:177], v[198:201], v[102:105]
	v_mfma_f32_16x16x32_bf16 v[94:97], v[182:185], v[198:201], v[94:97]
	v_mfma_f32_16x16x32_bf16 v[86:89], v[174:177], v[206:209], v[86:89]
	v_mfma_f32_16x16x32_bf16 v[78:81], v[182:185], v[206:209], v[78:81]
	v_mfma_f32_16x16x32_bf16 v[70:73], v[174:177], v[214:217], v[70:73]
	v_mfma_f32_16x16x32_bf16 v[66:69], v[182:185], v[214:217], v[66:69]
	s_setprio 0
	s_barrier
	s_add_i32 s4, s67, s58
	s_mov_b32 m0, s4
	ds_read_b128 v[186:189], v152 offset:16384
	ds_read_b128 v[190:193], v152 offset:17408
	ds_read_b128 v[194:197], v152 offset:18432
	ds_read_b128 v[198:201], v152 offset:19456
	ds_read_b128 v[202:205], v152 offset:20480
	ds_read_b128 v[206:209], v152 offset:21504
	ds_read_b128 v[210:213], v152 offset:22528
	ds_read_b128 v[214:217], v152 offset:23552
	global_load_lds_dwordx4 v132, s[48:49]
	s_add_i32 m0, s4, 0x2000
	s_add_u32 s4, s48, 0x80000
	s_addc_u32 s5, s49, 0
	s_add_i32 s79, s68, s58
	global_load_lds_dwordx4 v136, s[48:49]
	s_mov_b32 m0, s79
	s_nop 0
	global_load_lds_dwordx4 v132, s[4:5]
	s_add_i32 m0, s79, 0x2000
	s_nop 0
	global_load_lds_dwordx4 v136, s[4:5]
	s_waitcnt vmcnt(6)
	s_waitcnt lgkmcnt(0)
	s_barrier
	s_setprio 1
	s_waitcnt lgkmcnt(0)
	v_mfma_f32_16x16x32_bf16 v[62:65], v[154:157], v[186:189], v[62:65]
	v_mfma_f32_16x16x32_bf16 v[58:61], v[162:165], v[186:189], v[58:61]
	v_mfma_f32_16x16x32_bf16 v[50:53], v[154:157], v[194:197], v[50:53]
	v_mfma_f32_16x16x32_bf16 v[42:45], v[162:165], v[194:197], v[42:45]
	v_mfma_f32_16x16x32_bf16 v[34:37], v[154:157], v[202:205], v[34:37]
	v_mfma_f32_16x16x32_bf16 v[26:29], v[162:165], v[202:205], v[26:29]
	v_mfma_f32_16x16x32_bf16 v[18:21], v[154:157], v[210:213], v[18:21]
	v_mfma_f32_16x16x32_bf16 v[10:13], v[162:165], v[210:213], v[10:13]
	v_mfma_f32_16x16x32_bf16 v[62:65], v[158:161], v[190:193], v[62:65]
	v_mfma_f32_16x16x32_bf16 v[58:61], v[166:169], v[190:193], v[58:61]
	v_mfma_f32_16x16x32_bf16 v[50:53], v[158:161], v[198:201], v[50:53]
	v_mfma_f32_16x16x32_bf16 v[42:45], v[166:169], v[198:201], v[42:45]
	v_mfma_f32_16x16x32_bf16 v[34:37], v[158:161], v[206:209], v[34:37]
	v_mfma_f32_16x16x32_bf16 v[26:29], v[166:169], v[206:209], v[26:29]
	v_mfma_f32_16x16x32_bf16 v[18:21], v[158:161], v[214:217], v[18:21]
	v_mfma_f32_16x16x32_bf16 v[10:13], v[166:169], v[214:217], v[10:13]
	s_setprio 0
	s_setprio 1
	v_mfma_f32_16x16x32_bf16 v[54:57], v[170:173], v[186:189], v[54:57]
	v_mfma_f32_16x16x32_bf16 v[46:49], v[178:181], v[186:189], v[46:49]
	v_mfma_f32_16x16x32_bf16 v[38:41], v[170:173], v[194:197], v[38:41]
	v_mfma_f32_16x16x32_bf16 v[30:33], v[178:181], v[194:197], v[30:33]
	v_mfma_f32_16x16x32_bf16 v[22:25], v[170:173], v[202:205], v[22:25]
	v_mfma_f32_16x16x32_bf16 v[14:17], v[178:181], v[202:205], v[14:17]
	v_mfma_f32_16x16x32_bf16 v[6:9], v[170:173], v[210:213], v[6:9]
	v_mfma_f32_16x16x32_bf16 v[2:5], v[178:181], v[210:213], v[2:5]
	v_mfma_f32_16x16x32_bf16 v[54:57], v[174:177], v[190:193], v[54:57]
	v_mfma_f32_16x16x32_bf16 v[46:49], v[182:185], v[190:193], v[46:49]
	v_mfma_f32_16x16x32_bf16 v[38:41], v[174:177], v[198:201], v[38:41]
	v_mfma_f32_16x16x32_bf16 v[30:33], v[182:185], v[198:201], v[30:33]
	v_mfma_f32_16x16x32_bf16 v[22:25], v[174:177], v[206:209], v[22:25]
	v_mfma_f32_16x16x32_bf16 v[14:17], v[182:185], v[206:209], v[14:17]
	v_mfma_f32_16x16x32_bf16 v[6:9], v[174:177], v[214:217], v[6:9]
	v_mfma_f32_16x16x32_bf16 v[2:5], v[182:185], v[214:217], v[2:5]
	s_setprio 0
	s_barrier
; #define PG8_STAGE(bufoff, gbase, voff) do { _Pragma("unroll") for (int _i = 0; _i < 2; ++_i) \
;         __builtin_amdgcn_global_load_lds((const unsigned*)((const char*)(gbase) + (voff)[_i]), (PG8_LAS unsigned*)(lds + (bufoff) + ldsw + _i * 8192), 16, 0, 0); } while (0)
; #define PG8_LDA(dst, b, h) do { _Pragma("unroll") for (int m = 0; m < 4; ++m) _Pragma("unroll") for (int k = 0; k < 2; ++k) dst[m][k] = *(const PG8_LAS bf16x8*)(lds + PG8_SA(b, h) + aoff + m * 2048 + k * 1024); } while (0)
; #define PG8_LDB(dst, b, h) do { _Pragma("unroll") for (int n = 0; n < 2; ++n) _Pragma("unroll") for (int k = 0; k < 2; ++k) dst[n][k] = *(const PG8_LAS bf16x8*)(lds + PG8_SB(b, h) + boff + n * 2048 + k * 1024); } while (0)
; #define PG8_MMA(ai, bj, At, Bt) do { __builtin_amdgcn_s_setprio(1); _Pragma("unroll") for (int m = 0; m < 4; ++m) _Pragma("unroll") for (int n = 0; n < 2; ++n) _Pragma("unroll") for (int k = 0; k < 2; ++k) \
;         acc[ai][bj][m][n] = __builtin_amdgcn_mfma_f32_16x16x32_bf16(Bt[n][k], At[m][k], acc[ai][bj][m][n], 0, 0, 0); __builtin_amdgcn_s_setprio(0); } while (0)
; #define PG8_WAIT_V(n) asm volatile("s_waitcnt vmcnt(" #n ")" ::: "memory")
; #define PG8_WAIT_L(n) asm volatile("s_waitcnt lgkmcnt(" #n ")" ::: "memory")
; #define PG8_BAR __builtin_amdgcn_s_barrier()
; #define PG8_SCHED __builtin_amdgcn_sched_barrier(0)
; template <class Epi, class Sched, bool ALIGN_EPI = false, bool SP2 = false>
; __device__ __forceinline__ void gemm_phase(PG8_LAS unsigned char* lds, const Gemm g, const Sched& S, const Epi& E) {
;     ...
;             PG8_LDB(B0, 1, 0); PG8_LDB(B1, 1, 1); PG8_SCHED; PG8_LDA(At, 1, 0); PG8_STAGE(PG8_SA(0, 1), a2 + hstep, voffA);
;             PG8_WAIT_V(8); PG8_WAIT_L(0); PG8_BAR; PG8_MMA(0, 0, At, B0); PG8_MMA(0, 1, At, B1); PG8_BAR; PG8_SCHED;
;             PG8_LDA(At, 1, 1); PG8_STAGE(PG8_SB(1, 0), b3, voffB); PG8_STAGE(PG8_SB(1, 1), b3 + hstep, voffB); PG8_STAGE(PG8_SA(1, 0), a3, voffA);
;             PG8_WAIT_V(8); PG8_WAIT_L(0); PG8_BAR; PG8_MMA(1, 0, At, B0); PG8_MMA(1, 1, At, B1); PG8_BAR; PG8_SCHED;
	s_add_i32 s79, 0, 0x18000
	v_add_u32_e32 v153, s79, v148
	s_add_i32 s80, 0, 0x1c000
	ds_read_b128 v[154:157], v153
	ds_read_b128 v[158:161], v153 offset:1024
	ds_read_b128 v[162:165], v153 offset:2048
	ds_read_b128 v[166:169], v153 offset:3072
	v_add_u32_e32 v153, s80, v148
	ds_read_b128 v[170:173], v153
	ds_read_b128 v[174:177], v153 offset:1024
	ds_read_b128 v[178:181], v153 offset:2048
	ds_read_b128 v[182:185], v153 offset:3072
	s_add_u32 s4, s50, 0x80000
	s_addc_u32 s5, s51, 0
	s_mov_b32 m0, s39
	s_nop 0
	global_load_lds_dwordx4 v130, s[50:51]
	s_mov_b32 m0, s59
	s_nop 0
	global_load_lds_dwordx4 v134, s[50:51]
	s_mov_b32 m0, s60
	ds_read_b128 v[186:189], v152 offset:32768
	ds_read_b128 v[190:193], v152 offset:33792
	ds_read_b128 v[194:197], v152 offset:34816
	ds_read_b128 v[198:201], v152 offset:35840
	ds_read_b128 v[202:205], v152 offset:36864
	ds_read_b128 v[206:209], v152 offset:37888
	ds_read_b128 v[210:213], v152 offset:38912
	ds_read_b128 v[214:217], v152 offset:39936
	global_load_lds_dwordx4 v130, s[4:5]
	s_mov_b32 m0, s61
	s_nop 0
	global_load_lds_dwordx4 v134, s[4:5]
	s_waitcnt vmcnt(8)
	s_waitcnt lgkmcnt(0)
	s_barrier
	s_setprio 1
	s_waitcnt lgkmcnt(0)
	v_mfma_f32_16x16x32_bf16 v[126:129], v[154:157], v[186:189], v[126:129]
	v_mfma_f32_16x16x32_bf16 v[122:125], v[162:165], v[186:189], v[122:125]
	v_mfma_f32_16x16x32_bf16 v[114:117], v[154:157], v[194:197], v[114:117]
	v_mfma_f32_16x16x32_bf16 v[106:109], v[162:165], v[194:197], v[106:109]
	v_mfma_f32_16x16x32_bf16 v[98:101], v[154:157], v[202:205], v[98:101]
	v_mfma_f32_16x16x32_bf16 v[90:93], v[162:165], v[202:205], v[90:93]
	v_mfma_f32_16x16x32_bf16 v[82:85], v[154:157], v[210:213], v[82:85]
	v_mfma_f32_16x16x32_bf16 v[74:77], v[162:165], v[210:213], v[74:77]
	v_mfma_f32_16x16x32_bf16 v[126:129], v[158:161], v[190:193], v[126:129]
	v_mfma_f32_16x16x32_bf16 v[122:125], v[166:169], v[190:193], v[122:125]
	v_mfma_f32_16x16x32_bf16 v[114:117], v[158:161], v[198:201], v[114:117]
	v_mfma_f32_16x16x32_bf16 v[106:109], v[166:169], v[198:201], v[106:109]
	v_mfma_f32_16x16x32_bf16 v[98:101], v[158:161], v[206:209], v[98:101]
	v_mfma_f32_16x16x32_bf16 v[90:93], v[166:169], v[206:209], v[90:93]
	v_mfma_f32_16x16x32_bf16 v[82:85], v[158:161], v[214:217], v[82:85]
	v_mfma_f32_16x16x32_bf16 v[74:77], v[166:169], v[214:217], v[74:77]
	s_setprio 0
	s_setprio 1
	v_mfma_f32_16x16x32_bf16 v[118:121], v[170:173], v[186:189], v[118:121]
	v_mfma_f32_16x16x32_bf16 v[110:113], v[178:181], v[186:189], v[110:113]
	v_mfma_f32_16x16x32_bf16 v[102:105], v[170:173], v[194:197], v[102:105]
	v_mfma_f32_16x16x32_bf16 v[94:97], v[178:181], v[194:197], v[94:97]
	v_mfma_f32_16x16x32_bf16 v[86:89], v[170:173], v[202:205], v[86:89]
	v_mfma_f32_16x16x32_bf16 v[78:81], v[178:181], v[202:205], v[78:81]
	v_mfma_f32_16x16x32_bf16 v[70:73], v[170:173], v[210:213], v[70:73]
	v_mfma_f32_16x16x32_bf16 v[66:69], v[178:181], v[210:213], v[66:69]
	v_mfma_f32_16x16x32_bf16 v[118:121], v[174:177], v[190:193], v[118:121]
	v_mfma_f32_16x16x32_bf16 v[110:113], v[182:185], v[190:193], v[110:113]
	v_mfma_f32_16x16x32_bf16 v[102:105], v[174:177], v[198:201], v[102:105]
	v_mfma_f32_16x16x32_bf16 v[94:97], v[182:185], v[198:201], v[94:97]
	v_mfma_f32_16x16x32_bf16 v[86:89], v[174:177], v[206:209], v[86:89]
	v_mfma_f32_16x16x32_bf16 v[78:81], v[182:185], v[206:209], v[78:81]
	v_mfma_f32_16x16x32_bf16 v[70:73], v[174:177], v[214:217], v[70:73]
	v_mfma_f32_16x16x32_bf16 v[66:69], v[182:185], v[214:217], v[66:69]
	s_setprio 0
	s_barrier
	s_add_i32 s4, s79, s58
	s_add_i32 m0, s4, 0xffffff80
	ds_read_b128 v[186:189], v152 offset:49152
	ds_read_b128 v[190:193], v152 offset:50176
	ds_read_b128 v[194:197], v152 offset:51200
	ds_read_b128 v[198:201], v152 offset:52224
	ds_read_b128 v[202:205], v152 offset:53248
	ds_read_b128 v[206:209], v152 offset:54272
	ds_read_b128 v[210:213], v152 offset:55296
	ds_read_b128 v[214:217], v152 offset:56320
	global_load_lds_dwordx4 v132, s[48:49] offset:128
	s_add_i32 m0, s4, 0x1f80
	s_add_u32 s4, s48, 0x80080
	s_addc_u32 s5, s49, 0
	global_load_lds_dwordx4 v136, s[48:49] offset:128
	s_add_i32 s48, s80, s58
	s_mov_b32 m0, s48
	s_nop 0
	global_load_lds_dwordx4 v132, s[4:5]
	s_add_i32 m0, s48, 0x2000
	s_nop 0
	global_load_lds_dwordx4 v136, s[4:5]
	s_waitcnt vmcnt(6)
	s_waitcnt lgkmcnt(0)
	s_barrier
	s_setprio 1
	s_waitcnt lgkmcnt(0)
	v_mfma_f32_16x16x32_bf16 v[62:65], v[154:157], v[186:189], v[62:65]
	v_mfma_f32_16x16x32_bf16 v[58:61], v[162:165], v[186:189], v[58:61]
	v_mfma_f32_16x16x32_bf16 v[50:53], v[154:157], v[194:197], v[50:53]
	v_mfma_f32_16x16x32_bf16 v[42:45], v[162:165], v[194:197], v[42:45]
	v_mfma_f32_16x16x32_bf16 v[34:37], v[154:157], v[202:205], v[34:37]
	v_mfma_f32_16x16x32_bf16 v[26:29], v[162:165], v[202:205], v[26:29]
	v_mfma_f32_16x16x32_bf16 v[18:21], v[154:157], v[210:213], v[18:21]
	v_mfma_f32_16x16x32_bf16 v[10:13], v[162:165], v[210:213], v[10:13]
	v_mfma_f32_16x16x32_bf16 v[62:65], v[158:161], v[190:193], v[62:65]
	v_mfma_f32_16x16x32_bf16 v[58:61], v[166:169], v[190:193], v[58:61]
	v_mfma_f32_16x16x32_bf16 v[50:53], v[158:161], v[198:201], v[50:53]
	v_mfma_f32_16x16x32_bf16 v[42:45], v[166:169], v[198:201], v[42:45]
	v_mfma_f32_16x16x32_bf16 v[34:37], v[158:161], v[206:209], v[34:37]
	v_mfma_f32_16x16x32_bf16 v[26:29], v[166:169], v[206:209], v[26:29]
	v_mfma_f32_16x16x32_bf16 v[18:21], v[158:161], v[214:217], v[18:21]
	v_mfma_f32_16x16x32_bf16 v[10:13], v[166:169], v[214:217], v[10:13]
	s_setprio 0
	s_setprio 1
	v_mfma_f32_16x16x32_bf16 v[54:57], v[170:173], v[186:189], v[54:57]
	v_mfma_f32_16x16x32_bf16 v[46:49], v[178:181], v[186:189], v[46:49]
	v_mfma_f32_16x16x32_bf16 v[38:41], v[170:173], v[194:197], v[38:41]
	v_mfma_f32_16x16x32_bf16 v[30:33], v[178:181], v[194:197], v[30:33]
	v_mfma_f32_16x16x32_bf16 v[22:25], v[170:173], v[202:205], v[22:25]
	v_mfma_f32_16x16x32_bf16 v[14:17], v[178:181], v[202:205], v[14:17]
	v_mfma_f32_16x16x32_bf16 v[6:9], v[170:173], v[210:213], v[6:9]
	v_mfma_f32_16x16x32_bf16 v[2:5], v[178:181], v[210:213], v[2:5]
	v_mfma_f32_16x16x32_bf16 v[54:57], v[174:177], v[190:193], v[54:57]
	v_mfma_f32_16x16x32_bf16 v[46:49], v[182:185], v[190:193], v[46:49]
	v_mfma_f32_16x16x32_bf16 v[38:41], v[174:177], v[198:201], v[38:41]
	v_mfma_f32_16x16x32_bf16 v[30:33], v[182:185], v[198:201], v[30:33]
	v_mfma_f32_16x16x32_bf16 v[22:25], v[174:177], v[206:209], v[22:25]
	v_mfma_f32_16x16x32_bf16 v[14:17], v[182:185], v[206:209], v[14:17]
	v_mfma_f32_16x16x32_bf16 v[6:9], v[174:177], v[214:217], v[6:9]
	v_mfma_f32_16x16x32_bf16 v[2:5], v[182:185], v[214:217], v[2:5]
	s_setprio 0
	s_barrier
	s_add_i32 s78, s78, 2
	s_add_u32 s40, s40, 0x100
	s_addc_u32 s41, s41, 0
	s_add_u32 s76, s76, 0x100
	s_addc_u32 s77, s77, 0
	s_cmp_gt_u32 s78, 29
	s_cbranch_scc0 .LBB0_763
	s_and_b64 vcc, exec, s[20:21]
	s_cbranch_vccz .LBB0_766
	s_barrier

; #define PG8_STAGE(bufoff, gbase, voff) do { _Pragma("unroll") for (int _i = 0; _i < 2; ++_i) \
;         __builtin_amdgcn_global_load_lds((const unsigned*)((const char*)(gbase) + (voff)[_i]), (PG8_LAS unsigned*)(lds + (bufoff) + ldsw + _i * 8192), 16, 0, 0); } while (0)
; #define PG8_LDA(dst, b, h) do { _Pragma("unroll") for (int m = 0; m < 4; ++m) _Pragma("unroll") for (int k = 0; k < 2; ++k) dst[m][k] = *(const PG8_LAS bf16x8*)(lds + PG8_SA(b, h) + aoff + m * 2048 + k * 1024); } while (0)
; #define PG8_LDB(dst, b, h) do { _Pragma("unroll") for (int n = 0; n < 2; ++n) _Pragma("unroll") for (int k = 0; k < 2; ++k) dst[n][k] = *(const PG8_LAS bf16x8*)(lds + PG8_SB(b, h) + boff + n * 2048 + k * 1024); } while (0)
; #define PG8_MMA(ai, bj, At, Bt) do { __builtin_amdgcn_s_setprio(1); _Pragma("unroll") for (int m = 0; m < 4; ++m) _Pragma("unroll") for (int n = 0; n < 2; ++n) _Pragma("unroll") for (int k = 0; k < 2; ++k) \
;         acc[ai][bj][m][n] = __builtin_amdgcn_mfma_f32_16x16x32_bf16(Bt[n][k], At[m][k], acc[ai][bj][m][n], 0, 0, 0); __builtin_amdgcn_s_setprio(0); } while (0)
; #define PG8_WAIT_V(n) asm volatile("s_waitcnt vmcnt(" #n ")" ::: "memory")
; #define PG8_WAIT_L(n) asm volatile("s_waitcnt lgkmcnt(" #n ")" ::: "memory")
; #define PG8_BAR __builtin_amdgcn_s_barrier()
; #define PG8_SCHED __builtin_amdgcn_sched_barrier(0)
; template <class Epi, class Sched, bool ALIGN_EPI = false, bool SP2 = false>
; __device__ __forceinline__ void gemm_phase(PG8_LAS unsigned char* lds, const Gemm g, const Sched& S, const Epi& E) {
;     ...
;             PG8_LDB(B0, 0, 0); PG8_LDB(B1, 0, 1); PG8_SCHED; PG8_LDA(At, 0, 0); PG8_STAGE(PG8_SA(1, 1), a1 + hstep, voffA);
;             PG8_WAIT_V(8); PG8_WAIT_L(0); PG8_BAR; PG8_MMA(0, 0, At, B0); PG8_MMA(0, 1, At, B1); PG8_BAR; PG8_SCHED;
;             PG8_LDA(At, 0, 1); PG8_STAGE(PG8_SB(0, 0), b2, voffB); PG8_STAGE(PG8_SB(0, 1), b2 + hstep, voffB); PG8_STAGE(PG8_SA(0, 0), a2, voffA);
;             PG8_WAIT_V(8); PG8_WAIT_L(0); PG8_BAR; PG8_MMA(1, 0, At, B0); PG8_MMA(1, 1, At, B1); PG8_BAR; PG8_SCHED;
.LBB0_913:
	ds_read_b128 v[156:159], v152
	ds_read_b128 v[160:163], v152 offset:1024
	ds_read_b128 v[164:167], v152 offset:2048
	ds_read_b128 v[168:171], v152 offset:3072
	ds_read_b128 v[172:175], v153
	ds_read_b128 v[176:179], v153 offset:1024
	ds_read_b128 v[180:183], v153 offset:2048
	ds_read_b128 v[184:187], v153 offset:3072
	s_add_u32 s4, s34, 0xfff80080
	s_addc_u32 s5, s35, -1
	s_cmp_eq_u32 s69, 28
	s_cselect_b32 s39, s25, s5
	s_cselect_b32 s38, s65, s4
	s_cselect_b32 s37, s23, s68
	s_cselect_b32 s36, s66, s67
	s_add_i32 m0, s53, 0x80
	s_nop 0
	global_load_lds_dwordx4 v136, s[4:5] offset:-128
	s_add_i32 m0, s58, 0x80
	s_nop 0
	global_load_lds_dwordx4 v132, s[4:5] offset:-128
	s_add_i32 m0, s31, 0xc000
	ds_read_b128 v[188:191], v154
	ds_read_b128 v[192:195], v154 offset:1024
	ds_read_b128 v[196:199], v154 offset:2048
	ds_read_b128 v[200:203], v154 offset:3072
	ds_read_b128 v[204:207], v154 offset:4096
	ds_read_b128 v[208:211], v154 offset:5120
	ds_read_b128 v[212:215], v154 offset:6144
	ds_read_b128 v[216:219], v154 offset:7168
	global_load_lds_dwordx4 v138, s[34:35]
	s_add_i32 m0, s31, 0xe000
	s_nop 0
	global_load_lds_dwordx4 v140, s[34:35]
	s_waitcnt vmcnt(8)
	s_waitcnt lgkmcnt(0)
	s_barrier
	s_setprio 1
	s_waitcnt lgkmcnt(0)
	v_mfma_f32_16x16x32_bf16 v[126:129], v[156:159], v[188:191], v[126:129]
	v_mfma_f32_16x16x32_bf16 v[122:125], v[164:167], v[188:191], v[122:125]
	v_mfma_f32_16x16x32_bf16 v[110:113], v[156:159], v[196:199], v[110:113]
	v_mfma_f32_16x16x32_bf16 v[106:109], v[164:167], v[196:199], v[106:109]
	v_mfma_f32_16x16x32_bf16 v[94:97], v[156:159], v[204:207], v[94:97]
	v_mfma_f32_16x16x32_bf16 v[90:93], v[164:167], v[204:207], v[90:93]
	v_mfma_f32_16x16x32_bf16 v[78:81], v[156:159], v[212:215], v[78:81]
	v_mfma_f32_16x16x32_bf16 v[74:77], v[164:167], v[212:215], v[74:77]
	v_mfma_f32_16x16x32_bf16 v[126:129], v[160:163], v[192:195], v[126:129]
	v_mfma_f32_16x16x32_bf16 v[122:125], v[168:171], v[192:195], v[122:125]
	v_mfma_f32_16x16x32_bf16 v[110:113], v[160:163], v[200:203], v[110:113]
	v_mfma_f32_16x16x32_bf16 v[106:109], v[168:171], v[200:203], v[106:109]
	v_mfma_f32_16x16x32_bf16 v[94:97], v[160:163], v[208:211], v[94:97]
	v_mfma_f32_16x16x32_bf16 v[90:93], v[168:171], v[208:211], v[90:93]
	v_mfma_f32_16x16x32_bf16 v[78:81], v[160:163], v[216:219], v[78:81]
	v_mfma_f32_16x16x32_bf16 v[74:77], v[168:171], v[216:219], v[74:77]
	s_setprio 0
	s_setprio 1
	v_mfma_f32_16x16x32_bf16 v[118:121], v[172:175], v[188:191], v[118:121]
	v_mfma_f32_16x16x32_bf16 v[114:117], v[180:183], v[188:191], v[114:117]
	v_mfma_f32_16x16x32_bf16 v[102:105], v[172:175], v[196:199], v[102:105]
	v_mfma_f32_16x16x32_bf16 v[98:101], v[180:183], v[196:199], v[98:101]
	v_mfma_f32_16x16x32_bf16 v[86:89], v[172:175], v[204:207], v[86:89]
	v_mfma_f32_16x16x32_bf16 v[82:85], v[180:183], v[204:207], v[82:85]
	v_mfma_f32_16x16x32_bf16 v[70:73], v[172:175], v[212:215], v[70:73]
	v_mfma_f32_16x16x32_bf16 v[66:69], v[180:183], v[212:215], v[66:69]
	v_mfma_f32_16x16x32_bf16 v[118:121], v[176:179], v[192:195], v[118:121]
	v_mfma_f32_16x16x32_bf16 v[114:117], v[184:187], v[192:195], v[114:117]
	v_mfma_f32_16x16x32_bf16 v[102:105], v[176:179], v[200:203], v[102:105]
	v_mfma_f32_16x16x32_bf16 v[98:101], v[184:187], v[200:203], v[98:101]
	v_mfma_f32_16x16x32_bf16 v[86:89], v[176:179], v[208:211], v[86:89]
	v_mfma_f32_16x16x32_bf16 v[82:85], v[184:187], v[208:211], v[82:85]
	v_mfma_f32_16x16x32_bf16 v[70:73], v[176:179], v[216:219], v[70:73]
	v_mfma_f32_16x16x32_bf16 v[66:69], v[184:187], v[216:219], v[66:69]
	s_setprio 0
	s_barrier
	s_add_i32 s4, s61, s40
	s_mov_b32 m0, s4
	ds_read_b128 v[188:191], v154 offset:16384
	ds_read_b128 v[192:195], v154 offset:17408
	ds_read_b128 v[196:199], v154 offset:18432
	ds_read_b128 v[200:203], v154 offset:19456
	ds_read_b128 v[204:207], v154 offset:20480
	ds_read_b128 v[208:211], v154 offset:21504
	ds_read_b128 v[212:215], v154 offset:22528
	ds_read_b128 v[216:219], v154 offset:23552
	global_load_lds_dwordx4 v134, s[36:37]
	s_add_i32 m0, s4, 0x2000
	s_add_u32 s4, s36, 0x80000
	s_addc_u32 s5, s37, 0
	s_add_i32 s70, s62, s40
	global_load_lds_dwordx4 v130, s[36:37]
	s_mov_b32 m0, s70
	s_nop 0
	global_load_lds_dwordx4 v134, s[4:5]
	s_add_i32 m0, s70, 0x2000
	s_nop 0
	global_load_lds_dwordx4 v130, s[4:5]
	s_waitcnt vmcnt(6)
	s_waitcnt lgkmcnt(0)
	s_barrier
	s_setprio 1
	s_waitcnt lgkmcnt(0)
	v_mfma_f32_16x16x32_bf16 v[62:65], v[156:159], v[188:191], v[62:65]
	v_mfma_f32_16x16x32_bf16 v[58:61], v[164:167], v[188:191], v[58:61]
	v_mfma_f32_16x16x32_bf16 v[46:49], v[156:159], v[196:199], v[46:49]
	v_mfma_f32_16x16x32_bf16 v[42:45], v[164:167], v[196:199], v[42:45]
	v_mfma_f32_16x16x32_bf16 v[30:33], v[156:159], v[204:207], v[30:33]
	v_mfma_f32_16x16x32_bf16 v[26:29], v[164:167], v[204:207], v[26:29]
	v_mfma_f32_16x16x32_bf16 v[14:17], v[156:159], v[212:215], v[14:17]
	v_mfma_f32_16x16x32_bf16 v[10:13], v[164:167], v[212:215], v[10:13]
	v_mfma_f32_16x16x32_bf16 v[62:65], v[160:163], v[192:195], v[62:65]
	v_mfma_f32_16x16x32_bf16 v[58:61], v[168:171], v[192:195], v[58:61]
	v_mfma_f32_16x16x32_bf16 v[46:49], v[160:163], v[200:203], v[46:49]
	v_mfma_f32_16x16x32_bf16 v[42:45], v[168:171], v[200:203], v[42:45]
	v_mfma_f32_16x16x32_bf16 v[30:33], v[160:163], v[208:211], v[30:33]
	v_mfma_f32_16x16x32_bf16 v[26:29], v[168:171], v[208:211], v[26:29]
	v_mfma_f32_16x16x32_bf16 v[14:17], v[160:163], v[216:219], v[14:17]
	v_mfma_f32_16x16x32_bf16 v[10:13], v[168:171], v[216:219], v[10:13]
	s_setprio 0
	s_setprio 1
	v_mfma_f32_16x16x32_bf16 v[54:57], v[172:175], v[188:191], v[54:57]
	v_mfma_f32_16x16x32_bf16 v[50:53], v[180:183], v[188:191], v[50:53]
	v_mfma_f32_16x16x32_bf16 v[38:41], v[172:175], v[196:199], v[38:41]
	v_mfma_f32_16x16x32_bf16 v[34:37], v[180:183], v[196:199], v[34:37]
	v_mfma_f32_16x16x32_bf16 v[22:25], v[172:175], v[204:207], v[22:25]
	v_mfma_f32_16x16x32_bf16 v[18:21], v[180:183], v[204:207], v[18:21]
	v_mfma_f32_16x16x32_bf16 v[6:9], v[172:175], v[212:215], v[6:9]
	v_mfma_f32_16x16x32_bf16 v[2:5], v[180:183], v[212:215], v[2:5]
	v_mfma_f32_16x16x32_bf16 v[54:57], v[176:179], v[192:195], v[54:57]
	v_mfma_f32_16x16x32_bf16 v[50:53], v[184:187], v[192:195], v[50:53]
	v_mfma_f32_16x16x32_bf16 v[38:41], v[176:179], v[200:203], v[38:41]
	v_mfma_f32_16x16x32_bf16 v[34:37], v[184:187], v[200:203], v[34:37]
	v_mfma_f32_16x16x32_bf16 v[22:25], v[176:179], v[208:211], v[22:25]
	v_mfma_f32_16x16x32_bf16 v[18:21], v[184:187], v[208:211], v[18:21]
	v_mfma_f32_16x16x32_bf16 v[6:9], v[176:179], v[216:219], v[6:9]
	v_mfma_f32_16x16x32_bf16 v[2:5], v[184:187], v[216:219], v[2:5]
	s_setprio 0
	s_barrier
; #define PG8_STAGE(bufoff, gbase, voff) do { _Pragma("unroll") for (int _i = 0; _i < 2; ++_i) \
;         __builtin_amdgcn_global_load_lds((const unsigned*)((const char*)(gbase) + (voff)[_i]), (PG8_LAS unsigned*)(lds + (bufoff) + ldsw + _i * 8192), 16, 0, 0); } while (0)
; #define PG8_LDA(dst, b, h) do { _Pragma("unroll") for (int m = 0; m < 4; ++m) _Pragma("unroll") for (int k = 0; k < 2; ++k) dst[m][k] = *(const PG8_LAS bf16x8*)(lds + PG8_SA(b, h) + aoff + m * 2048 + k * 1024); } while (0)
; #define PG8_LDB(dst, b, h) do { _Pragma("unroll") for (int n = 0; n < 2; ++n) _Pragma("unroll") for (int k = 0; k < 2; ++k) dst[n][k] = *(const PG8_LAS bf16x8*)(lds + PG8_SB(b, h) + boff + n * 2048 + k * 1024); } while (0)
; #define PG8_MMA(ai, bj, At, Bt) do { __builtin_amdgcn_s_setprio(1); _Pragma("unroll") for (int m = 0; m < 4; ++m) _Pragma("unroll") for (int n = 0; n < 2; ++n) _Pragma("unroll") for (int k = 0; k < 2; ++k) \
;         acc[ai][bj][m][n] = __builtin_amdgcn_mfma_f32_16x16x32_bf16(Bt[n][k], At[m][k], acc[ai][bj][m][n], 0, 0, 0); __builtin_amdgcn_s_setprio(0); } while (0)
; #define PG8_WAIT_V(n) asm volatile("s_waitcnt vmcnt(" #n ")" ::: "memory")
; #define PG8_WAIT_L(n) asm volatile("s_waitcnt lgkmcnt(" #n ")" ::: "memory")
; #define PG8_BAR __builtin_amdgcn_s_barrier()
; #define PG8_SCHED __builtin_amdgcn_sched_barrier(0)
; template <class Epi, class Sched, bool ALIGN_EPI = false, bool SP2 = false>
; __device__ __forceinline__ void gemm_phase(PG8_LAS unsigned char* lds, const Gemm g, const Sched& S, const Epi& E) {
;     ...
;             PG8_LDB(B0, 1, 0); PG8_LDB(B1, 1, 1); PG8_SCHED; PG8_LDA(At, 1, 0); PG8_STAGE(PG8_SA(0, 1), a2 + hstep, voffA);
;             PG8_WAIT_V(8); PG8_WAIT_L(0); PG8_BAR; PG8_MMA(0, 0, At, B0); PG8_MMA(0, 1, At, B1); PG8_BAR; PG8_SCHED;
;             PG8_LDA(At, 1, 1); PG8_STAGE(PG8_SB(1, 0), b3, voffB); PG8_STAGE(PG8_SB(1, 1), b3 + hstep, voffB); PG8_STAGE(PG8_SA(1, 0), a3, voffA);
;             PG8_WAIT_V(8); PG8_WAIT_L(0); PG8_BAR; PG8_MMA(1, 0, At, B0); PG8_MMA(1, 1, At, B1); PG8_BAR; PG8_SCHED;
	s_add_i32 s70, 0, 0x18000
	v_add_u32_e32 v155, s70, v150
	s_add_i32 s71, 0, 0x1c000
	ds_read_b128 v[156:159], v155
	ds_read_b128 v[160:163], v155 offset:1024
	ds_read_b128 v[164:167], v155 offset:2048
	ds_read_b128 v[168:171], v155 offset:3072
	v_add_u32_e32 v155, s71, v150
	ds_read_b128 v[172:175], v155
	ds_read_b128 v[176:179], v155 offset:1024
	ds_read_b128 v[180:183], v155 offset:2048
	ds_read_b128 v[184:187], v155 offset:3072
	s_add_u32 s4, s38, 0x80000
	s_addc_u32 s5, s39, 0
	s_mov_b32 m0, s31
	s_nop 0
	global_load_lds_dwordx4 v136, s[38:39]
	s_mov_b32 m0, s49
	s_nop 0
	global_load_lds_dwordx4 v132, s[38:39]
	s_mov_b32 m0, s50
	ds_read_b128 v[188:191], v154 offset:32768
	ds_read_b128 v[192:195], v154 offset:33792
	ds_read_b128 v[196:199], v154 offset:34816
	ds_read_b128 v[200:203], v154 offset:35840
	ds_read_b128 v[204:207], v154 offset:36864
	ds_read_b128 v[208:211], v154 offset:37888
	ds_read_b128 v[212:215], v154 offset:38912
	ds_read_b128 v[216:219], v154 offset:39936
	global_load_lds_dwordx4 v136, s[4:5]
	s_mov_b32 m0, s51
	s_nop 0
	global_load_lds_dwordx4 v132, s[4:5]
	s_waitcnt vmcnt(8)
	s_waitcnt lgkmcnt(0)
	s_barrier
	s_setprio 1
	s_waitcnt lgkmcnt(0)
	v_mfma_f32_16x16x32_bf16 v[126:129], v[156:159], v[188:191], v[126:129]
	v_mfma_f32_16x16x32_bf16 v[122:125], v[164:167], v[188:191], v[122:125]
	v_mfma_f32_16x16x32_bf16 v[110:113], v[156:159], v[196:199], v[110:113]
	v_mfma_f32_16x16x32_bf16 v[106:109], v[164:167], v[196:199], v[106:109]
	v_mfma_f32_16x16x32_bf16 v[94:97], v[156:159], v[204:207], v[94:97]
	v_mfma_f32_16x16x32_bf16 v[90:93], v[164:167], v[204:207], v[90:93]
	v_mfma_f32_16x16x32_bf16 v[78:81], v[156:159], v[212:215], v[78:81]
	v_mfma_f32_16x16x32_bf16 v[74:77], v[164:167], v[212:215], v[74:77]
	v_mfma_f32_16x16x32_bf16 v[126:129], v[160:163], v[192:195], v[126:129]
	v_mfma_f32_16x16x32_bf16 v[122:125], v[168:171], v[192:195], v[122:125]
	v_mfma_f32_16x16x32_bf16 v[110:113], v[160:163], v[200:203], v[110:113]
	v_mfma_f32_16x16x32_bf16 v[106:109], v[168:171], v[200:203], v[106:109]
	v_mfma_f32_16x16x32_bf16 v[94:97], v[160:163], v[208:211], v[94:97]
	v_mfma_f32_16x16x32_bf16 v[90:93], v[168:171], v[208:211], v[90:93]
	v_mfma_f32_16x16x32_bf16 v[78:81], v[160:163], v[216:219], v[78:81]
	v_mfma_f32_16x16x32_bf16 v[74:77], v[168:171], v[216:219], v[74:77]
	s_setprio 0
	s_setprio 1
	v_mfma_f32_16x16x32_bf16 v[118:121], v[172:175], v[188:191], v[118:121]
	v_mfma_f32_16x16x32_bf16 v[114:117], v[180:183], v[188:191], v[114:117]
	v_mfma_f32_16x16x32_bf16 v[102:105], v[172:175], v[196:199], v[102:105]
	v_mfma_f32_16x16x32_bf16 v[98:101], v[180:183], v[196:199], v[98:101]
	v_mfma_f32_16x16x32_bf16 v[86:89], v[172:175], v[204:207], v[86:89]
	v_mfma_f32_16x16x32_bf16 v[82:85], v[180:183], v[204:207], v[82:85]
	v_mfma_f32_16x16x32_bf16 v[70:73], v[172:175], v[212:215], v[70:73]
	v_mfma_f32_16x16x32_bf16 v[66:69], v[180:183], v[212:215], v[66:69]
	v_mfma_f32_16x16x32_bf16 v[118:121], v[176:179], v[192:195], v[118:121]
	v_mfma_f32_16x16x32_bf16 v[114:117], v[184:187], v[192:195], v[114:117]
	v_mfma_f32_16x16x32_bf16 v[102:105], v[176:179], v[200:203], v[102:105]
	v_mfma_f32_16x16x32_bf16 v[98:101], v[184:187], v[200:203], v[98:101]
	v_mfma_f32_16x16x32_bf16 v[86:89], v[176:179], v[208:211], v[86:89]
	v_mfma_f32_16x16x32_bf16 v[82:85], v[184:187], v[208:211], v[82:85]
	v_mfma_f32_16x16x32_bf16 v[70:73], v[176:179], v[216:219], v[70:73]
	v_mfma_f32_16x16x32_bf16 v[66:69], v[184:187], v[216:219], v[66:69]
	s_setprio 0
	s_barrier
	s_add_i32 s4, s70, s40
	s_add_i32 m0, s4, 0xffffff80
	ds_read_b128 v[188:191], v154 offset:49152
	ds_read_b128 v[192:195], v154 offset:50176
	ds_read_b128 v[196:199], v154 offset:51200
	ds_read_b128 v[200:203], v154 offset:52224
	ds_read_b128 v[204:207], v154 offset:53248
	ds_read_b128 v[208:211], v154 offset:54272
	ds_read_b128 v[212:215], v154 offset:55296
	ds_read_b128 v[216:219], v154 offset:56320
	global_load_lds_dwordx4 v134, s[36:37] offset:128
	s_add_i32 m0, s4, 0x1f80
	s_add_u32 s4, s36, 0x80080
	s_addc_u32 s5, s37, 0
	global_load_lds_dwordx4 v130, s[36:37] offset:128
	s_add_i32 s36, s71, s40
	s_mov_b32 m0, s36
	s_nop 0
	global_load_lds_dwordx4 v134, s[4:5]
	s_add_i32 m0, s36, 0x2000
	s_nop 0
	global_load_lds_dwordx4 v130, s[4:5]
	s_waitcnt vmcnt(6)
	s_waitcnt lgkmcnt(0)
	s_barrier
	s_setprio 1
	s_waitcnt lgkmcnt(0)
	v_mfma_f32_16x16x32_bf16 v[62:65], v[156:159], v[188:191], v[62:65]
	v_mfma_f32_16x16x32_bf16 v[58:61], v[164:167], v[188:191], v[58:61]
	v_mfma_f32_16x16x32_bf16 v[46:49], v[156:159], v[196:199], v[46:49]
	v_mfma_f32_16x16x32_bf16 v[42:45], v[164:167], v[196:199], v[42:45]
	v_mfma_f32_16x16x32_bf16 v[30:33], v[156:159], v[204:207], v[30:33]
	v_mfma_f32_16x16x32_bf16 v[26:29], v[164:167], v[204:207], v[26:29]
	v_mfma_f32_16x16x32_bf16 v[14:17], v[156:159], v[212:215], v[14:17]
	v_mfma_f32_16x16x32_bf16 v[10:13], v[164:167], v[212:215], v[10:13]
	v_mfma_f32_16x16x32_bf16 v[62:65], v[160:163], v[192:195], v[62:65]
	v_mfma_f32_16x16x32_bf16 v[58:61], v[168:171], v[192:195], v[58:61]
	v_mfma_f32_16x16x32_bf16 v[46:49], v[160:163], v[200:203], v[46:49]
	v_mfma_f32_16x16x32_bf16 v[42:45], v[168:171], v[200:203], v[42:45]
	v_mfma_f32_16x16x32_bf16 v[30:33], v[160:163], v[208:211], v[30:33]
	v_mfma_f32_16x16x32_bf16 v[26:29], v[168:171], v[208:211], v[26:29]
	v_mfma_f32_16x16x32_bf16 v[14:17], v[160:163], v[216:219], v[14:17]
	v_mfma_f32_16x16x32_bf16 v[10:13], v[168:171], v[216:219], v[10:13]
	s_setprio 0
	s_setprio 1
	v_mfma_f32_16x16x32_bf16 v[54:57], v[172:175], v[188:191], v[54:57]
	v_mfma_f32_16x16x32_bf16 v[50:53], v[180:183], v[188:191], v[50:53]
	v_mfma_f32_16x16x32_bf16 v[38:41], v[172:175], v[196:199], v[38:41]
	v_mfma_f32_16x16x32_bf16 v[34:37], v[180:183], v[196:199], v[34:37]
	v_mfma_f32_16x16x32_bf16 v[22:25], v[172:175], v[204:207], v[22:25]
	v_mfma_f32_16x16x32_bf16 v[18:21], v[180:183], v[204:207], v[18:21]
	v_mfma_f32_16x16x32_bf16 v[6:9], v[172:175], v[212:215], v[6:9]
	v_mfma_f32_16x16x32_bf16 v[2:5], v[180:183], v[212:215], v[2:5]
	v_mfma_f32_16x16x32_bf16 v[54:57], v[176:179], v[192:195], v[54:57]
	v_mfma_f32_16x16x32_bf16 v[50:53], v[184:187], v[192:195], v[50:53]
	v_mfma_f32_16x16x32_bf16 v[38:41], v[176:179], v[200:203], v[38:41]
	v_mfma_f32_16x16x32_bf16 v[34:37], v[184:187], v[200:203], v[34:37]
	v_mfma_f32_16x16x32_bf16 v[22:25], v[176:179], v[208:211], v[22:25]
	v_mfma_f32_16x16x32_bf16 v[18:21], v[184:187], v[208:211], v[18:21]
	v_mfma_f32_16x16x32_bf16 v[6:9], v[176:179], v[216:219], v[6:9]
	v_mfma_f32_16x16x32_bf16 v[2:5], v[184:187], v[216:219], v[2:5]
	s_setprio 0
	s_barrier
	s_add_i32 s69, s69, 2
	s_add_u32 s34, s34, 0x100
	s_addc_u32 s35, s35, 0
	s_add_u32 s67, s67, 0x100
	s_addc_u32 s68, s68, 0
	s_cmp_gt_u32 s69, 29
	s_cbranch_scc0 .LBB0_913
	s_and_b64 vcc, exec, s[20:21]
	s_cbranch_vccz .LBB0_916
	s_barrier

; #define PG8_STAGE(bufoff, gbase, voff) do { _Pragma("unroll") for (int _i = 0; _i < 2; ++_i) \
;         __builtin_amdgcn_global_load_lds((const unsigned*)((const char*)(gbase) + (voff)[_i]), (PG8_LAS unsigned*)(lds + (bufoff) + ldsw + _i * 8192), 16, 0, 0); } while (0)
; #define PG8_LDA(dst, b, h) do { _Pragma("unroll") for (int m = 0; m < 4; ++m) _Pragma("unroll") for (int k = 0; k < 2; ++k) dst[m][k] = *(const PG8_LAS bf16x8*)(lds + PG8_SA(b, h) + aoff + m * 2048 + k * 1024); } while (0)
; #define PG8_LDB(dst, b, h) do { _Pragma("unroll") for (int n = 0; n < 2; ++n) _Pragma("unroll") for (int k = 0; k < 2; ++k) dst[n][k] = *(const PG8_LAS bf16x8*)(lds + PG8_SB(b, h) + boff + n * 2048 + k * 1024); } while (0)
; #define PG8_MMA(ai, bj, At, Bt) do { __builtin_amdgcn_s_setprio(1); _Pragma("unroll") for (int m = 0; m < 4; ++m) _Pragma("unroll") for (int n = 0; n < 2; ++n) _Pragma("unroll") for (int k = 0; k < 2; ++k) \
;         acc[ai][bj][m][n] = __builtin_amdgcn_mfma_f32_16x16x32_bf16(Bt[n][k], At[m][k], acc[ai][bj][m][n], 0, 0, 0); __builtin_amdgcn_s_setprio(0); } while (0)
; #define PG8_WAIT_V(n) asm volatile("s_waitcnt vmcnt(" #n ")" ::: "memory")
; #define PG8_WAIT_L(n) asm volatile("s_waitcnt lgkmcnt(" #n ")" ::: "memory")
; #define PG8_BAR __builtin_amdgcn_s_barrier()
; #define PG8_SCHED __builtin_amdgcn_sched_barrier(0)
; template <class Epi, class Sched, bool ALIGN_EPI = false, bool SP2 = false>
; __device__ __forceinline__ void gemm_phase(PG8_LAS unsigned char* lds, const Gemm g, const Sched& S, const Epi& E) {
;     ...
;             PG8_LDB(B0, 0, 0); PG8_LDB(B1, 0, 1); PG8_SCHED; PG8_LDA(At, 0, 0); PG8_STAGE(PG8_SA(1, 1), a1 + hstep, voffA);
;             PG8_WAIT_V(8); PG8_WAIT_L(0); PG8_BAR; PG8_MMA(0, 0, At, B0); PG8_MMA(0, 1, At, B1); PG8_BAR; PG8_SCHED;
;             PG8_LDA(At, 0, 1); PG8_STAGE(PG8_SB(0, 0), b2, voffB); PG8_STAGE(PG8_SB(0, 1), b2 + hstep, voffB); PG8_STAGE(PG8_SA(0, 0), a2, voffA);
;             PG8_WAIT_V(8); PG8_WAIT_L(0); PG8_BAR; PG8_MMA(1, 0, At, B0); PG8_MMA(1, 1, At, B1); PG8_BAR; PG8_SCHED;
.LBB0_1017:
	ds_read_b128 v[154:157], v150
	ds_read_b128 v[158:161], v150 offset:1024
	ds_read_b128 v[162:165], v150 offset:2048
	ds_read_b128 v[166:169], v150 offset:3072
	ds_read_b128 v[170:173], v151
	ds_read_b128 v[174:177], v151 offset:1024
	ds_read_b128 v[178:181], v151 offset:2048
	ds_read_b128 v[182:185], v151 offset:3072
	s_add_u32 s34, s30, 0x100
	s_addc_u32 s35, s31, 0
	s_cmpk_eq_i32 s74, 0x54
	s_cselect_b32 s39, s9, s35
	s_cselect_b32 s38, s8, s34
	s_cselect_b32 s37, s29, s73
	s_cselect_b32 s36, s28, s72
	s_add_i32 m0, s58, 0x80
	s_nop 0
	global_load_lds_dwordx4 v130, s[34:35] offset:-128
	s_add_i32 m0, s59, 0x80
	s_nop 0
	global_load_lds_dwordx4 v134, s[34:35] offset:-128
	s_add_i32 m0, s49, 0xc000
	ds_read_b128 v[186:189], v152
	ds_read_b128 v[190:193], v152 offset:1024
	ds_read_b128 v[194:197], v152 offset:2048
	ds_read_b128 v[198:201], v152 offset:3072
	ds_read_b128 v[202:205], v152 offset:4096
	ds_read_b128 v[206:209], v152 offset:5120
	ds_read_b128 v[210:213], v152 offset:6144
	ds_read_b128 v[214:217], v152 offset:7168
	global_load_lds_dwordx4 v138, s[30:31]
	s_add_i32 m0, s49, 0xe000
	s_nop 0
	global_load_lds_dwordx4 v140, s[30:31]
	s_waitcnt vmcnt(8)
	s_waitcnt lgkmcnt(0)
	s_barrier
	s_setprio 1
	s_waitcnt lgkmcnt(0)
	v_mfma_f32_16x16x32_bf16 v[126:129], v[154:157], v[186:189], v[126:129]
	v_mfma_f32_16x16x32_bf16 v[122:125], v[162:165], v[186:189], v[122:125]
	v_mfma_f32_16x16x32_bf16 v[114:117], v[154:157], v[194:197], v[114:117]
	v_mfma_f32_16x16x32_bf16 v[106:109], v[162:165], v[194:197], v[106:109]
	v_mfma_f32_16x16x32_bf16 v[98:101], v[154:157], v[202:205], v[98:101]
	v_mfma_f32_16x16x32_bf16 v[90:93], v[162:165], v[202:205], v[90:93]
	v_mfma_f32_16x16x32_bf16 v[82:85], v[154:157], v[210:213], v[82:85]
	v_mfma_f32_16x16x32_bf16 v[74:77], v[162:165], v[210:213], v[74:77]
	v_mfma_f32_16x16x32_bf16 v[126:129], v[158:161], v[190:193], v[126:129]
	v_mfma_f32_16x16x32_bf16 v[122:125], v[166:169], v[190:193], v[122:125]
	v_mfma_f32_16x16x32_bf16 v[114:117], v[158:161], v[198:201], v[114:117]
	v_mfma_f32_16x16x32_bf16 v[106:109], v[166:169], v[198:201], v[106:109]
	v_mfma_f32_16x16x32_bf16 v[98:101], v[158:161], v[206:209], v[98:101]
	v_mfma_f32_16x16x32_bf16 v[90:93], v[166:169], v[206:209], v[90:93]
	v_mfma_f32_16x16x32_bf16 v[82:85], v[158:161], v[214:217], v[82:85]
	v_mfma_f32_16x16x32_bf16 v[74:77], v[166:169], v[214:217], v[74:77]
	s_setprio 0
	s_setprio 1
	v_mfma_f32_16x16x32_bf16 v[118:121], v[170:173], v[186:189], v[118:121]
	v_mfma_f32_16x16x32_bf16 v[110:113], v[178:181], v[186:189], v[110:113]
	v_mfma_f32_16x16x32_bf16 v[102:105], v[170:173], v[194:197], v[102:105]
	v_mfma_f32_16x16x32_bf16 v[94:97], v[178:181], v[194:197], v[94:97]
	v_mfma_f32_16x16x32_bf16 v[86:89], v[170:173], v[202:205], v[86:89]
	v_mfma_f32_16x16x32_bf16 v[78:81], v[178:181], v[202:205], v[78:81]
	v_mfma_f32_16x16x32_bf16 v[70:73], v[170:173], v[210:213], v[70:73]
	v_mfma_f32_16x16x32_bf16 v[66:69], v[178:181], v[210:213], v[66:69]
	v_mfma_f32_16x16x32_bf16 v[118:121], v[174:177], v[190:193], v[118:121]
	v_mfma_f32_16x16x32_bf16 v[110:113], v[182:185], v[190:193], v[110:113]
	v_mfma_f32_16x16x32_bf16 v[102:105], v[174:177], v[198:201], v[102:105]
	v_mfma_f32_16x16x32_bf16 v[94:97], v[182:185], v[198:201], v[94:97]
	v_mfma_f32_16x16x32_bf16 v[86:89], v[174:177], v[206:209], v[86:89]
	v_mfma_f32_16x16x32_bf16 v[78:81], v[182:185], v[206:209], v[78:81]
	v_mfma_f32_16x16x32_bf16 v[70:73], v[174:177], v[214:217], v[70:73]
	v_mfma_f32_16x16x32_bf16 v[66:69], v[182:185], v[214:217], v[66:69]
	s_setprio 0
	s_barrier
	s_add_i32 s4, s62, s48
	s_mov_b32 m0, s4
	ds_read_b128 v[186:189], v152 offset:16384
	ds_read_b128 v[190:193], v152 offset:17408
	ds_read_b128 v[194:197], v152 offset:18432
	ds_read_b128 v[198:201], v152 offset:19456
	ds_read_b128 v[202:205], v152 offset:20480
	ds_read_b128 v[206:209], v152 offset:21504
	ds_read_b128 v[210:213], v152 offset:22528
	ds_read_b128 v[214:217], v152 offset:23552
	global_load_lds_dwordx4 v132, s[36:37]
	s_add_i32 m0, s4, 0x2000
	s_add_u32 s4, s36, 0x160000
	s_addc_u32 s5, s37, 0
	s_add_i32 s30, s63, s48
	global_load_lds_dwordx4 v136, s[36:37]
	s_mov_b32 m0, s30
	s_nop 0
	global_load_lds_dwordx4 v132, s[4:5]
	s_add_i32 m0, s30, 0x2000
	s_nop 0
	global_load_lds_dwordx4 v136, s[4:5]
	s_waitcnt vmcnt(6)
	s_waitcnt lgkmcnt(0)
	s_barrier
	s_setprio 1
	s_waitcnt lgkmcnt(0)
	v_mfma_f32_16x16x32_bf16 v[62:65], v[154:157], v[186:189], v[62:65]
	v_mfma_f32_16x16x32_bf16 v[58:61], v[162:165], v[186:189], v[58:61]
	v_mfma_f32_16x16x32_bf16 v[50:53], v[154:157], v[194:197], v[50:53]
	v_mfma_f32_16x16x32_bf16 v[42:45], v[162:165], v[194:197], v[42:45]
	v_mfma_f32_16x16x32_bf16 v[34:37], v[154:157], v[202:205], v[34:37]
	v_mfma_f32_16x16x32_bf16 v[26:29], v[162:165], v[202:205], v[26:29]
	v_mfma_f32_16x16x32_bf16 v[18:21], v[154:157], v[210:213], v[18:21]
	v_mfma_f32_16x16x32_bf16 v[10:13], v[162:165], v[210:213], v[10:13]
	v_mfma_f32_16x16x32_bf16 v[62:65], v[158:161], v[190:193], v[62:65]
	v_mfma_f32_16x16x32_bf16 v[58:61], v[166:169], v[190:193], v[58:61]
	v_mfma_f32_16x16x32_bf16 v[50:53], v[158:161], v[198:201], v[50:53]
	v_mfma_f32_16x16x32_bf16 v[42:45], v[166:169], v[198:201], v[42:45]
	v_mfma_f32_16x16x32_bf16 v[34:37], v[158:161], v[206:209], v[34:37]
	v_mfma_f32_16x16x32_bf16 v[26:29], v[166:169], v[206:209], v[26:29]
	v_mfma_f32_16x16x32_bf16 v[18:21], v[158:161], v[214:217], v[18:21]
	v_mfma_f32_16x16x32_bf16 v[10:13], v[166:169], v[214:217], v[10:13]
	s_setprio 0
	s_setprio 1
	v_mfma_f32_16x16x32_bf16 v[54:57], v[170:173], v[186:189], v[54:57]
	v_mfma_f32_16x16x32_bf16 v[46:49], v[178:181], v[186:189], v[46:49]
	v_mfma_f32_16x16x32_bf16 v[38:41], v[170:173], v[194:197], v[38:41]
	v_mfma_f32_16x16x32_bf16 v[30:33], v[178:181], v[194:197], v[30:33]
	v_mfma_f32_16x16x32_bf16 v[22:25], v[170:173], v[202:205], v[22:25]
	v_mfma_f32_16x16x32_bf16 v[14:17], v[178:181], v[202:205], v[14:17]
	v_mfma_f32_16x16x32_bf16 v[6:9], v[170:173], v[210:213], v[6:9]
	v_mfma_f32_16x16x32_bf16 v[2:5], v[178:181], v[210:213], v[2:5]
	v_mfma_f32_16x16x32_bf16 v[54:57], v[174:177], v[190:193], v[54:57]
	v_mfma_f32_16x16x32_bf16 v[46:49], v[182:185], v[190:193], v[46:49]
	v_mfma_f32_16x16x32_bf16 v[38:41], v[174:177], v[198:201], v[38:41]
	v_mfma_f32_16x16x32_bf16 v[30:33], v[182:185], v[198:201], v[30:33]
	v_mfma_f32_16x16x32_bf16 v[22:25], v[174:177], v[206:209], v[22:25]
	v_mfma_f32_16x16x32_bf16 v[14:17], v[182:185], v[206:209], v[14:17]
	v_mfma_f32_16x16x32_bf16 v[6:9], v[174:177], v[214:217], v[6:9]
	v_mfma_f32_16x16x32_bf16 v[2:5], v[182:185], v[214:217], v[2:5]
	s_setprio 0
	s_barrier
; #define PG8_STAGE(bufoff, gbase, voff) do { _Pragma("unroll") for (int _i = 0; _i < 2; ++_i) \
;         __builtin_amdgcn_global_load_lds((const unsigned*)((const char*)(gbase) + (voff)[_i]), (PG8_LAS unsigned*)(lds + (bufoff) + ldsw + _i * 8192), 16, 0, 0); } while (0)
; #define PG8_LDA(dst, b, h) do { _Pragma("unroll") for (int m = 0; m < 4; ++m) _Pragma("unroll") for (int k = 0; k < 2; ++k) dst[m][k] = *(const PG8_LAS bf16x8*)(lds + PG8_SA(b, h) + aoff + m * 2048 + k * 1024); } while (0)
; #define PG8_LDB(dst, b, h) do { _Pragma("unroll") for (int n = 0; n < 2; ++n) _Pragma("unroll") for (int k = 0; k < 2; ++k) dst[n][k] = *(const PG8_LAS bf16x8*)(lds + PG8_SB(b, h) + boff + n * 2048 + k * 1024); } while (0)
; #define PG8_MMA(ai, bj, At, Bt) do { __builtin_amdgcn_s_setprio(1); _Pragma("unroll") for (int m = 0; m < 4; ++m) _Pragma("unroll") for (int n = 0; n < 2; ++n) _Pragma("unroll") for (int k = 0; k < 2; ++k) \
;         acc[ai][bj][m][n] = __builtin_amdgcn_mfma_f32_16x16x32_bf16(Bt[n][k], At[m][k], acc[ai][bj][m][n], 0, 0, 0); __builtin_amdgcn_s_setprio(0); } while (0)
; #define PG8_WAIT_V(n) asm volatile("s_waitcnt vmcnt(" #n ")" ::: "memory")
; #define PG8_WAIT_L(n) asm volatile("s_waitcnt lgkmcnt(" #n ")" ::: "memory")
; #define PG8_BAR __builtin_amdgcn_s_barrier()
; #define PG8_SCHED __builtin_amdgcn_sched_barrier(0)
; template <class Epi, class Sched, bool ALIGN_EPI = false, bool SP2 = false>
; __device__ __forceinline__ void gemm_phase(PG8_LAS unsigned char* lds, const Gemm g, const Sched& S, const Epi& E) {
;     ...
;             PG8_LDB(B0, 1, 0); PG8_LDB(B1, 1, 1); PG8_SCHED; PG8_LDA(At, 1, 0); PG8_STAGE(PG8_SA(0, 1), a2 + hstep, voffA);
;             PG8_WAIT_V(8); PG8_WAIT_L(0); PG8_BAR; PG8_MMA(0, 0, At, B0); PG8_MMA(0, 1, At, B1); PG8_BAR; PG8_SCHED;
;             PG8_LDA(At, 1, 1); PG8_STAGE(PG8_SB(1, 0), b3, voffB); PG8_STAGE(PG8_SB(1, 1), b3 + hstep, voffB); PG8_STAGE(PG8_SA(1, 0), a3, voffA);
;             PG8_WAIT_V(8); PG8_WAIT_L(0); PG8_BAR; PG8_MMA(1, 0, At, B0); PG8_MMA(1, 1, At, B1); PG8_BAR; PG8_SCHED;
	s_add_i32 s30, 0, 0x18000
	v_add_u32_e32 v153, s30, v148
	s_add_i32 s31, 0, 0x1c000
	ds_read_b128 v[154:157], v153
	ds_read_b128 v[158:161], v153 offset:1024
	ds_read_b128 v[162:165], v153 offset:2048
	ds_read_b128 v[166:169], v153 offset:3072
	v_add_u32_e32 v153, s31, v148
	ds_read_b128 v[170:173], v153
	ds_read_b128 v[174:177], v153 offset:1024
	ds_read_b128 v[178:181], v153 offset:2048
	ds_read_b128 v[182:185], v153 offset:3072
	s_add_u32 s4, s38, 0x160000
	s_addc_u32 s5, s39, 0
	s_mov_b32 m0, s49
	s_nop 0
	global_load_lds_dwordx4 v130, s[38:39]
	s_mov_b32 m0, s50
	s_nop 0
	global_load_lds_dwordx4 v134, s[38:39]
	s_mov_b32 m0, s51
	ds_read_b128 v[186:189], v152 offset:32768
	ds_read_b128 v[190:193], v152 offset:33792
	ds_read_b128 v[194:197], v152 offset:34816
	ds_read_b128 v[198:201], v152 offset:35840
	ds_read_b128 v[202:205], v152 offset:36864
	ds_read_b128 v[206:209], v152 offset:37888
	ds_read_b128 v[210:213], v152 offset:38912
	ds_read_b128 v[214:217], v152 offset:39936
	global_load_lds_dwordx4 v130, s[4:5]
	s_mov_b32 m0, s52
	s_nop 0
	global_load_lds_dwordx4 v134, s[4:5]
	s_waitcnt vmcnt(8)
	s_waitcnt lgkmcnt(0)
	s_barrier
	s_setprio 1
	s_waitcnt lgkmcnt(0)
	v_mfma_f32_16x16x32_bf16 v[126:129], v[154:157], v[186:189], v[126:129]
	v_mfma_f32_16x16x32_bf16 v[122:125], v[162:165], v[186:189], v[122:125]
	v_mfma_f32_16x16x32_bf16 v[114:117], v[154:157], v[194:197], v[114:117]
	v_mfma_f32_16x16x32_bf16 v[106:109], v[162:165], v[194:197], v[106:109]
	v_mfma_f32_16x16x32_bf16 v[98:101], v[154:157], v[202:205], v[98:101]
	v_mfma_f32_16x16x32_bf16 v[90:93], v[162:165], v[202:205], v[90:93]
	v_mfma_f32_16x16x32_bf16 v[82:85], v[154:157], v[210:213], v[82:85]
	v_mfma_f32_16x16x32_bf16 v[74:77], v[162:165], v[210:213], v[74:77]
	v_mfma_f32_16x16x32_bf16 v[126:129], v[158:161], v[190:193], v[126:129]
	v_mfma_f32_16x16x32_bf16 v[122:125], v[166:169], v[190:193], v[122:125]
	v_mfma_f32_16x16x32_bf16 v[114:117], v[158:161], v[198:201], v[114:117]
	v_mfma_f32_16x16x32_bf16 v[106:109], v[166:169], v[198:201], v[106:109]
	v_mfma_f32_16x16x32_bf16 v[98:101], v[158:161], v[206:209], v[98:101]
	v_mfma_f32_16x16x32_bf16 v[90:93], v[166:169], v[206:209], v[90:93]
	v_mfma_f32_16x16x32_bf16 v[82:85], v[158:161], v[214:217], v[82:85]
	v_mfma_f32_16x16x32_bf16 v[74:77], v[166:169], v[214:217], v[74:77]
	s_setprio 0
	s_setprio 1
	v_mfma_f32_16x16x32_bf16 v[118:121], v[170:173], v[186:189], v[118:121]
	v_mfma_f32_16x16x32_bf16 v[110:113], v[178:181], v[186:189], v[110:113]
	v_mfma_f32_16x16x32_bf16 v[102:105], v[170:173], v[194:197], v[102:105]
	v_mfma_f32_16x16x32_bf16 v[94:97], v[178:181], v[194:197], v[94:97]
	v_mfma_f32_16x16x32_bf16 v[86:89], v[170:173], v[202:205], v[86:89]
	v_mfma_f32_16x16x32_bf16 v[78:81], v[178:181], v[202:205], v[78:81]
	v_mfma_f32_16x16x32_bf16 v[70:73], v[170:173], v[210:213], v[70:73]
	v_mfma_f32_16x16x32_bf16 v[66:69], v[178:181], v[210:213], v[66:69]
	v_mfma_f32_16x16x32_bf16 v[118:121], v[174:177], v[190:193], v[118:121]
	v_mfma_f32_16x16x32_bf16 v[110:113], v[182:185], v[190:193], v[110:113]
	v_mfma_f32_16x16x32_bf16 v[102:105], v[174:177], v[198:201], v[102:105]
	v_mfma_f32_16x16x32_bf16 v[94:97], v[182:185], v[198:201], v[94:97]
	v_mfma_f32_16x16x32_bf16 v[86:89], v[174:177], v[206:209], v[86:89]
	v_mfma_f32_16x16x32_bf16 v[78:81], v[182:185], v[206:209], v[78:81]
	v_mfma_f32_16x16x32_bf16 v[70:73], v[174:177], v[214:217], v[70:73]
	v_mfma_f32_16x16x32_bf16 v[66:69], v[182:185], v[214:217], v[66:69]
	s_setprio 0
	s_barrier
	s_add_i32 s4, s30, s48
	s_add_i32 m0, s4, 0xffffff80
	ds_read_b128 v[186:189], v152 offset:49152
	ds_read_b128 v[190:193], v152 offset:50176
	ds_read_b128 v[194:197], v152 offset:51200
	ds_read_b128 v[198:201], v152 offset:52224
	ds_read_b128 v[202:205], v152 offset:53248
	ds_read_b128 v[206:209], v152 offset:54272
	ds_read_b128 v[210:213], v152 offset:55296
	ds_read_b128 v[214:217], v152 offset:56320
	global_load_lds_dwordx4 v132, s[36:37] offset:128
	s_add_i32 m0, s4, 0x1f80
	s_add_u32 s4, s36, 0x160080
	s_addc_u32 s5, s37, 0
	s_add_i32 s30, s31, s48
	global_load_lds_dwordx4 v136, s[36:37] offset:128
	s_mov_b32 m0, s30
	s_nop 0
	global_load_lds_dwordx4 v132, s[4:5]
	s_add_i32 m0, s30, 0x2000
	s_nop 0
	global_load_lds_dwordx4 v136, s[4:5]
	s_waitcnt vmcnt(6)
	s_waitcnt lgkmcnt(0)
	s_barrier
	s_setprio 1
	s_waitcnt lgkmcnt(0)
	v_mfma_f32_16x16x32_bf16 v[62:65], v[154:157], v[186:189], v[62:65]
	v_mfma_f32_16x16x32_bf16 v[58:61], v[162:165], v[186:189], v[58:61]
	v_mfma_f32_16x16x32_bf16 v[50:53], v[154:157], v[194:197], v[50:53]
	v_mfma_f32_16x16x32_bf16 v[42:45], v[162:165], v[194:197], v[42:45]
	v_mfma_f32_16x16x32_bf16 v[34:37], v[154:157], v[202:205], v[34:37]
	v_mfma_f32_16x16x32_bf16 v[26:29], v[162:165], v[202:205], v[26:29]
	v_mfma_f32_16x16x32_bf16 v[18:21], v[154:157], v[210:213], v[18:21]
	v_mfma_f32_16x16x32_bf16 v[10:13], v[162:165], v[210:213], v[10:13]
	v_mfma_f32_16x16x32_bf16 v[62:65], v[158:161], v[190:193], v[62:65]
	v_mfma_f32_16x16x32_bf16 v[58:61], v[166:169], v[190:193], v[58:61]
	v_mfma_f32_16x16x32_bf16 v[50:53], v[158:161], v[198:201], v[50:53]
	v_mfma_f32_16x16x32_bf16 v[42:45], v[166:169], v[198:201], v[42:45]
	v_mfma_f32_16x16x32_bf16 v[34:37], v[158:161], v[206:209], v[34:37]
	v_mfma_f32_16x16x32_bf16 v[26:29], v[166:169], v[206:209], v[26:29]
	v_mfma_f32_16x16x32_bf16 v[18:21], v[158:161], v[214:217], v[18:21]
	v_mfma_f32_16x16x32_bf16 v[10:13], v[166:169], v[214:217], v[10:13]
	s_setprio 0
	s_setprio 1
	v_mfma_f32_16x16x32_bf16 v[54:57], v[170:173], v[186:189], v[54:57]
	v_mfma_f32_16x16x32_bf16 v[46:49], v[178:181], v[186:189], v[46:49]
	v_mfma_f32_16x16x32_bf16 v[38:41], v[170:173], v[194:197], v[38:41]
	v_mfma_f32_16x16x32_bf16 v[30:33], v[178:181], v[194:197], v[30:33]
	v_mfma_f32_16x16x32_bf16 v[22:25], v[170:173], v[202:205], v[22:25]
	v_mfma_f32_16x16x32_bf16 v[14:17], v[178:181], v[202:205], v[14:17]
	v_mfma_f32_16x16x32_bf16 v[6:9], v[170:173], v[210:213], v[6:9]
	v_mfma_f32_16x16x32_bf16 v[2:5], v[178:181], v[210:213], v[2:5]
	v_mfma_f32_16x16x32_bf16 v[54:57], v[174:177], v[190:193], v[54:57]
	v_mfma_f32_16x16x32_bf16 v[46:49], v[182:185], v[190:193], v[46:49]
	v_mfma_f32_16x16x32_bf16 v[38:41], v[174:177], v[198:201], v[38:41]
	v_mfma_f32_16x16x32_bf16 v[30:33], v[182:185], v[198:201], v[30:33]
	v_mfma_f32_16x16x32_bf16 v[22:25], v[174:177], v[206:209], v[22:25]
	v_mfma_f32_16x16x32_bf16 v[14:17], v[182:185], v[206:209], v[14:17]
	v_mfma_f32_16x16x32_bf16 v[6:9], v[174:177], v[214:217], v[6:9]
	v_mfma_f32_16x16x32_bf16 v[2:5], v[182:185], v[214:217], v[2:5]
	s_setprio 0
	s_barrier
	s_add_i32 s74, s74, 2
	s_add_u32 s72, s72, 0x100
	s_addc_u32 s73, s73, 0
	s_cmpk_gt_u32 s74, 0x55
	s_mov_b64 s[30:31], s[34:35]
	s_cbranch_scc0 .LBB0_1017
	s_and_b64 vcc, exec, s[18:19]
	s_cbranch_vccz .LBB0_1020
	s_barrier
